# v039 + GEMM K-loops (lever 9): loop-counter and pointer increments hoisted from between the last barrier and the next iteration's first ds_read into the preceding 32-MFMA block
# speedup vs baseline: 1.0079x; 1.0079x over previous
; #define PG8_STAGE(bufoff, gbase, voff) do { _Pragma("unroll") for (int _i = 0; _i < 2; ++_i) \
;         __builtin_amdgcn_global_load_lds((const unsigned*)((const char*)(gbase) + (voff)[_i]), (PG8_LAS unsigned*)(lds + (bufoff) + ldsw + _i * 8192), 16, 0, 0); } while (0)
; #define PG8_LDA(dst, b, h) do { _Pragma("unroll") for (int m = 0; m < 4; ++m) _Pragma("unroll") for (int k = 0; k < 2; ++k) dst[m][k] = *(const PG8_LAS bf16x8*)(lds + PG8_SA(b, h) + aoff + m * 2048 + k * 1024); } while (0)
; #define PG8_LDB(dst, b, h) do { _Pragma("unroll") for (int n = 0; n < 2; ++n) _Pragma("unroll") for (int k = 0; k < 2; ++k) dst[n][k] = *(const PG8_LAS bf16x8*)(lds + PG8_SB(b, h) + boff + n * 2048 + k * 1024); } while (0)
; #define PG8_MMA(ai, bj, At, Bt) do { __builtin_amdgcn_s_setprio(1); _Pragma("unroll") for (int m = 0; m < 4; ++m) _Pragma("unroll") for (int n = 0; n < 2; ++n) _Pragma("unroll") for (int k = 0; k < 2; ++k) \
;         acc[ai][bj][m][n] = __builtin_amdgcn_mfma_f32_16x16x32_bf16(Bt[n][k], At[m][k], acc[ai][bj][m][n], 0, 0, 0); __builtin_amdgcn_s_setprio(0); } while (0)
; #define PG8_WAIT_V(n) asm volatile("s_waitcnt vmcnt(" #n ")" ::: "memory")
; #define PG8_WAIT_L(n) asm volatile("s_waitcnt lgkmcnt(" #n ")" ::: "memory")
; #define PG8_BAR __builtin_amdgcn_s_barrier()
; #define PG8_SCHED __builtin_amdgcn_sched_barrier(0)
; template <class Epi, class Sched, bool ALIGN_EPI = false, bool SP2 = false>
; __device__ __forceinline__ void gemm_phase(PG8_LAS unsigned char* lds, const Gemm g, const Sched& S, const Epi& E) {
;     ...
;             PG8_LDB(B0, 0, 0); PG8_LDB(B1, 0, 1); PG8_SCHED; PG8_LDA(At, 0, 0); PG8_STAGE(PG8_SA(1, 1), a1 + hstep, voffA);
;             PG8_WAIT_V(8); PG8_WAIT_L(0); PG8_BAR; PG8_MMA(0, 0, At, B0); PG8_MMA(0, 1, At, B1); PG8_BAR; PG8_SCHED;
;             PG8_LDA(At, 0, 1); PG8_STAGE(PG8_SB(0, 0), b2, voffB); PG8_STAGE(PG8_SB(0, 1), b2 + hstep, voffB); PG8_STAGE(PG8_SA(0, 0), a2, voffA);
;             PG8_WAIT_V(8); PG8_WAIT_L(0); PG8_BAR; PG8_MMA(1, 0, At, B0); PG8_MMA(1, 1, At, B1); PG8_BAR; PG8_SCHED;
.LBB0_150:
	ds_read_b128 v[154:157], v150
	ds_read_b128 v[158:161], v150 offset:1024
	ds_read_b128 v[162:165], v150 offset:2048
	ds_read_b128 v[172:175], v150 offset:3072
	ds_read_b128 v[176:179], v151
	ds_read_b128 v[180:183], v151 offset:1024
	ds_read_b128 v[184:187], v151 offset:2048
	ds_read_b128 v[188:191], v151 offset:3072
	s_add_u32 s28, s0, 0xfffc0080
	s_addc_u32 s29, s1, -1
	s_cmp_eq_u32 s51, 12
	s_cselect_b32 s31, s21, s29
	s_cselect_b32 s30, s47, s28
	s_cselect_b32 s29, s19, s50
	s_cselect_b32 s28, s48, s49
	v_lshl_add_u64 v[144:145], s[0:1], 0, v[136:137]
	s_add_i32 m0, s27, 0xc000
	ds_read_b128 v[202:205], v152
	ds_read_b128 v[206:209], v152 offset:1024
	ds_read_b128 v[210:213], v152 offset:2048
	ds_read_b128 v[214:217], v152 offset:3072
	ds_read_b128 v[218:221], v152 offset:4096
	ds_read_b128 v[222:225], v152 offset:5120
	ds_read_b128 v[226:229], v152 offset:6144
	ds_read_b128 v[230:233], v152 offset:7168
	global_load_lds_dwordx4 v[144:145], off
	v_lshl_add_u64 v[144:145], s[0:1], 0, v[138:139]
	s_add_i32 m0, s27, 0xe000
	s_nop 0
	global_load_lds_dwordx4 v[144:145], off
	s_waitcnt vmcnt(8)
	s_waitcnt lgkmcnt(0)
	s_barrier
	s_setprio 1
	s_waitcnt lgkmcnt(0)
	v_mfma_f32_16x16x32_bf16 v[124:127], v[154:157], v[202:205], v[124:127]
	v_mfma_f32_16x16x32_bf16 v[120:123], v[162:165], v[202:205], v[120:123]
	v_mfma_f32_16x16x32_bf16 v[108:111], v[154:157], v[210:213], v[108:111]
	v_mfma_f32_16x16x32_bf16 v[104:107], v[162:165], v[210:213], v[104:107]
	v_mfma_f32_16x16x32_bf16 v[92:95], v[154:157], v[218:221], v[92:95]
	v_mfma_f32_16x16x32_bf16 v[88:91], v[162:165], v[218:221], v[88:91]
	v_mfma_f32_16x16x32_bf16 v[76:79], v[154:157], v[226:229], v[76:79]
	v_mfma_f32_16x16x32_bf16 v[72:75], v[162:165], v[226:229], v[72:75]
	v_mfma_f32_16x16x32_bf16 v[124:127], v[158:161], v[206:209], v[124:127]
	v_mfma_f32_16x16x32_bf16 v[120:123], v[172:175], v[206:209], v[120:123]
	v_mfma_f32_16x16x32_bf16 v[108:111], v[158:161], v[214:217], v[108:111]
	v_mfma_f32_16x16x32_bf16 v[104:107], v[172:175], v[214:217], v[104:107]
	v_mfma_f32_16x16x32_bf16 v[92:95], v[158:161], v[222:225], v[92:95]
	v_mfma_f32_16x16x32_bf16 v[88:91], v[172:175], v[222:225], v[88:91]
	v_mfma_f32_16x16x32_bf16 v[76:79], v[158:161], v[230:233], v[76:79]
	v_mfma_f32_16x16x32_bf16 v[72:75], v[172:175], v[230:233], v[72:75]
	s_setprio 0
	s_setprio 1
	v_mfma_f32_16x16x32_bf16 v[116:119], v[176:179], v[202:205], v[116:119]
	v_mfma_f32_16x16x32_bf16 v[112:115], v[184:187], v[202:205], v[112:115]
	v_mfma_f32_16x16x32_bf16 v[100:103], v[176:179], v[210:213], v[100:103]
	v_mfma_f32_16x16x32_bf16 v[96:99], v[184:187], v[210:213], v[96:99]
	v_mfma_f32_16x16x32_bf16 v[84:87], v[176:179], v[218:221], v[84:87]
	v_mfma_f32_16x16x32_bf16 v[80:83], v[184:187], v[218:221], v[80:83]
	v_mfma_f32_16x16x32_bf16 v[68:71], v[176:179], v[226:229], v[68:71]
	v_mfma_f32_16x16x32_bf16 v[64:67], v[184:187], v[226:229], v[64:67]
	v_mfma_f32_16x16x32_bf16 v[116:119], v[180:183], v[206:209], v[116:119]
	v_mfma_f32_16x16x32_bf16 v[112:115], v[188:191], v[206:209], v[112:115]
	v_mfma_f32_16x16x32_bf16 v[100:103], v[180:183], v[214:217], v[100:103]
	v_mfma_f32_16x16x32_bf16 v[96:99], v[188:191], v[214:217], v[96:99]
	v_mfma_f32_16x16x32_bf16 v[84:87], v[180:183], v[222:225], v[84:87]
	v_mfma_f32_16x16x32_bf16 v[80:83], v[188:191], v[222:225], v[80:83]
	v_mfma_f32_16x16x32_bf16 v[68:71], v[180:183], v[230:233], v[68:71]
	v_mfma_f32_16x16x32_bf16 v[64:67], v[188:191], v[230:233], v[64:67]
	s_setprio 0
	s_barrier
	s_add_i32 s52, s44, s34
	v_lshl_add_u64 v[144:145], s[28:29], 0, v[132:133]
	s_mov_b32 m0, s52
	ds_read_b128 v[202:205], v152 offset:16384
	ds_read_b128 v[206:209], v152 offset:17408
	ds_read_b128 v[210:213], v152 offset:18432
	ds_read_b128 v[214:217], v152 offset:19456
	ds_read_b128 v[218:221], v152 offset:20480
	ds_read_b128 v[222:225], v152 offset:21504
	ds_read_b128 v[226:229], v152 offset:22528
	ds_read_b128 v[230:233], v152 offset:23552
	global_load_lds_dwordx4 v[144:145], off
	s_add_i32 m0, s52, 0x2000
	s_add_u32 s52, s28, 0x40000
	v_lshl_add_u64 v[166:167], s[28:29], 0, v[128:129]
	s_addc_u32 s53, s29, 0
	s_add_i32 s54, s45, s34
	global_load_lds_dwordx4 v[166:167], off
	v_lshl_add_u64 v[192:193], s[52:53], 0, v[132:133]
	s_mov_b32 m0, s54
	v_lshl_add_u64 v[196:197], s[30:31], 0, v[130:131]
	global_load_lds_dwordx4 v[192:193], off
	v_lshl_add_u64 v[192:193], s[52:53], 0, v[128:129]
	s_add_i32 m0, s54, 0x2000
	s_nop 0
	global_load_lds_dwordx4 v[192:193], off
	v_lshl_add_u64 v[192:193], s[30:31], 0, v[134:135]
	s_mov_b32 m0, s27
	s_nop 0
	global_load_lds_dwordx4 v[192:193], off
	s_mov_b32 m0, s37
	s_nop 0
	global_load_lds_dwordx4 v[196:197], off
	s_waitcnt vmcnt(8)
	s_waitcnt lgkmcnt(0)
	s_barrier
; #define PG8_STAGE(bufoff, gbase, voff) do { _Pragma("unroll") for (int _i = 0; _i < 2; ++_i) \
;         __builtin_amdgcn_global_load_lds((const unsigned*)((const char*)(gbase) + (voff)[_i]), (PG8_LAS unsigned*)(lds + (bufoff) + ldsw + _i * 8192), 16, 0, 0); } while (0)
; #define PG8_LDA(dst, b, h) do { _Pragma("unroll") for (int m = 0; m < 4; ++m) _Pragma("unroll") for (int k = 0; k < 2; ++k) dst[m][k] = *(const PG8_LAS bf16x8*)(lds + PG8_SA(b, h) + aoff + m * 2048 + k * 1024); } while (0)
; #define PG8_LDB(dst, b, h) do { _Pragma("unroll") for (int n = 0; n < 2; ++n) _Pragma("unroll") for (int k = 0; k < 2; ++k) dst[n][k] = *(const PG8_LAS bf16x8*)(lds + PG8_SB(b, h) + boff + n * 2048 + k * 1024); } while (0)
; #define PG8_MMA(ai, bj, At, Bt) do { __builtin_amdgcn_s_setprio(1); _Pragma("unroll") for (int m = 0; m < 4; ++m) _Pragma("unroll") for (int n = 0; n < 2; ++n) _Pragma("unroll") for (int k = 0; k < 2; ++k) \
;         acc[ai][bj][m][n] = __builtin_amdgcn_mfma_f32_16x16x32_bf16(Bt[n][k], At[m][k], acc[ai][bj][m][n], 0, 0, 0); __builtin_amdgcn_s_setprio(0); } while (0)
; #define PG8_WAIT_V(n) asm volatile("s_waitcnt vmcnt(" #n ")" ::: "memory")
; #define PG8_WAIT_L(n) asm volatile("s_waitcnt lgkmcnt(" #n ")" ::: "memory")
; #define PG8_BAR __builtin_amdgcn_s_barrier()
; #define PG8_SCHED __builtin_amdgcn_sched_barrier(0)
; template <class Epi, class Sched, bool ALIGN_EPI = false, bool SP2 = false>
; __device__ __forceinline__ void gemm_phase(PG8_LAS unsigned char* lds, const Gemm g, const Sched& S, const Epi& E) {
;     ...
;             PG8_WAIT_V(8); PG8_WAIT_L(0); PG8_BAR; PG8_MMA(1, 0, At, B0); PG8_MMA(1, 1, At, B1); PG8_BAR; PG8_SCHED;
;             PG8_LDB(B0, 1, 0); PG8_LDB(B1, 1, 1); PG8_SCHED; PG8_LDA(At, 1, 0); PG8_STAGE(PG8_SA(0, 1), a2 + hstep, voffA);
;             PG8_WAIT_V(8); PG8_WAIT_L(0); PG8_BAR; PG8_MMA(0, 0, At, B0); PG8_MMA(0, 1, At, B1); PG8_BAR; PG8_SCHED;
	s_setprio 1
	s_waitcnt lgkmcnt(0)
	v_mfma_f32_16x16x32_bf16 v[60:63], v[154:157], v[202:205], v[60:63]
	v_mfma_f32_16x16x32_bf16 v[56:59], v[162:165], v[202:205], v[56:59]
	v_mfma_f32_16x16x32_bf16 v[44:47], v[154:157], v[210:213], v[44:47]
	v_mfma_f32_16x16x32_bf16 v[40:43], v[162:165], v[210:213], v[40:43]
	v_mfma_f32_16x16x32_bf16 v[28:31], v[154:157], v[218:221], v[28:31]
	v_mfma_f32_16x16x32_bf16 v[24:27], v[162:165], v[218:221], v[24:27]
	v_mfma_f32_16x16x32_bf16 v[12:15], v[154:157], v[226:229], v[12:15]
	v_mfma_f32_16x16x32_bf16 v[8:11], v[162:165], v[226:229], v[8:11]
	v_mfma_f32_16x16x32_bf16 v[60:63], v[158:161], v[206:209], v[60:63]
	v_mfma_f32_16x16x32_bf16 v[56:59], v[172:175], v[206:209], v[56:59]
	v_mfma_f32_16x16x32_bf16 v[44:47], v[158:161], v[214:217], v[44:47]
	v_mfma_f32_16x16x32_bf16 v[40:43], v[172:175], v[214:217], v[40:43]
	v_mfma_f32_16x16x32_bf16 v[28:31], v[158:161], v[222:225], v[28:31]
	v_mfma_f32_16x16x32_bf16 v[24:27], v[172:175], v[222:225], v[24:27]
	v_mfma_f32_16x16x32_bf16 v[12:15], v[158:161], v[230:233], v[12:15]
	v_mfma_f32_16x16x32_bf16 v[8:11], v[172:175], v[230:233], v[8:11]
	s_setprio 0
	s_setprio 1
	v_mfma_f32_16x16x32_bf16 v[52:55], v[176:179], v[202:205], v[52:55]
	v_mfma_f32_16x16x32_bf16 v[48:51], v[184:187], v[202:205], v[48:51]
	v_mfma_f32_16x16x32_bf16 v[36:39], v[176:179], v[210:213], v[36:39]
	v_mfma_f32_16x16x32_bf16 v[32:35], v[184:187], v[210:213], v[32:35]
	v_mfma_f32_16x16x32_bf16 v[20:23], v[176:179], v[218:221], v[20:23]
	v_mfma_f32_16x16x32_bf16 v[16:19], v[184:187], v[218:221], v[16:19]
	v_mfma_f32_16x16x32_bf16 v[4:7], v[176:179], v[226:229], v[4:7]
	v_mfma_f32_16x16x32_bf16 v[0:3], v[184:187], v[226:229], v[0:3]
	v_mfma_f32_16x16x32_bf16 v[52:55], v[180:183], v[206:209], v[52:55]
	v_mfma_f32_16x16x32_bf16 v[48:51], v[188:191], v[206:209], v[48:51]
	v_mfma_f32_16x16x32_bf16 v[36:39], v[180:183], v[214:217], v[36:39]
	v_mfma_f32_16x16x32_bf16 v[32:35], v[188:191], v[214:217], v[32:35]
	v_mfma_f32_16x16x32_bf16 v[20:23], v[180:183], v[222:225], v[20:23]
	v_mfma_f32_16x16x32_bf16 v[16:19], v[188:191], v[222:225], v[16:19]
	v_mfma_f32_16x16x32_bf16 v[4:7], v[180:183], v[230:233], v[4:7]
	v_mfma_f32_16x16x32_bf16 v[0:3], v[188:191], v[230:233], v[0:3]
	s_setprio 0
	s_barrier
	s_add_i32 s52, 0, 0x18000
	v_add_u32_e32 v153, s52, v147
	s_add_i32 s53, 0, 0x1c000
	ds_read_b128 v[154:157], v153
	ds_read_b128 v[158:161], v153 offset:1024
	ds_read_b128 v[162:165], v153 offset:2048
	ds_read_b128 v[172:175], v153 offset:3072
	v_add_u32_e32 v153, s53, v147
	ds_read_b128 v[176:179], v153
	ds_read_b128 v[180:183], v153 offset:1024
	ds_read_b128 v[184:187], v153 offset:2048
	ds_read_b128 v[188:191], v153 offset:3072
	s_add_u32 s30, s30, 0x40000
	s_addc_u32 s31, s31, 0
	s_mov_b32 m0, s38
	v_lshl_add_u64 v[234:235], s[30:31], 0, v[134:135]
	ds_read_b128 v[202:205], v152 offset:32768
	ds_read_b128 v[206:209], v152 offset:33792
	ds_read_b128 v[210:213], v152 offset:34816
	ds_read_b128 v[214:217], v152 offset:35840
	ds_read_b128 v[218:221], v152 offset:36864
	ds_read_b128 v[222:225], v152 offset:37888
	ds_read_b128 v[226:229], v152 offset:38912
	ds_read_b128 v[230:233], v152 offset:39936
	global_load_lds_dwordx4 v[234:235], off
	v_lshl_add_u64 v[234:235], s[30:31], 0, v[130:131]
	s_mov_b32 m0, s39
	s_nop 0
	global_load_lds_dwordx4 v[234:235], off
	s_waitcnt vmcnt(8)
	s_waitcnt lgkmcnt(0)
	s_barrier
	s_setprio 1
	s_waitcnt lgkmcnt(0)
	v_mfma_f32_16x16x32_bf16 v[124:127], v[154:157], v[202:205], v[124:127]
	v_mfma_f32_16x16x32_bf16 v[120:123], v[162:165], v[202:205], v[120:123]
	v_mfma_f32_16x16x32_bf16 v[108:111], v[154:157], v[210:213], v[108:111]
	v_mfma_f32_16x16x32_bf16 v[104:107], v[162:165], v[210:213], v[104:107]
	v_mfma_f32_16x16x32_bf16 v[92:95], v[154:157], v[218:221], v[92:95]
	v_mfma_f32_16x16x32_bf16 v[88:91], v[162:165], v[218:221], v[88:91]
	v_mfma_f32_16x16x32_bf16 v[76:79], v[154:157], v[226:229], v[76:79]
	v_mfma_f32_16x16x32_bf16 v[72:75], v[162:165], v[226:229], v[72:75]
	v_mfma_f32_16x16x32_bf16 v[124:127], v[158:161], v[206:209], v[124:127]
	v_mfma_f32_16x16x32_bf16 v[120:123], v[172:175], v[206:209], v[120:123]
	v_mfma_f32_16x16x32_bf16 v[108:111], v[158:161], v[214:217], v[108:111]
	v_mfma_f32_16x16x32_bf16 v[104:107], v[172:175], v[214:217], v[104:107]
	v_mfma_f32_16x16x32_bf16 v[92:95], v[158:161], v[222:225], v[92:95]
	v_mfma_f32_16x16x32_bf16 v[88:91], v[172:175], v[222:225], v[88:91]
	v_mfma_f32_16x16x32_bf16 v[76:79], v[158:161], v[230:233], v[76:79]
	v_mfma_f32_16x16x32_bf16 v[72:75], v[172:175], v[230:233], v[72:75]
	s_setprio 0
	s_setprio 1
	v_mfma_f32_16x16x32_bf16 v[116:119], v[176:179], v[202:205], v[116:119]
	v_mfma_f32_16x16x32_bf16 v[112:115], v[184:187], v[202:205], v[112:115]
	v_mfma_f32_16x16x32_bf16 v[100:103], v[176:179], v[210:213], v[100:103]
	v_mfma_f32_16x16x32_bf16 v[96:99], v[184:187], v[210:213], v[96:99]
	v_mfma_f32_16x16x32_bf16 v[84:87], v[176:179], v[218:221], v[84:87]
	v_mfma_f32_16x16x32_bf16 v[80:83], v[184:187], v[218:221], v[80:83]
	v_mfma_f32_16x16x32_bf16 v[68:71], v[176:179], v[226:229], v[68:71]
	v_mfma_f32_16x16x32_bf16 v[64:67], v[184:187], v[226:229], v[64:67]
	v_mfma_f32_16x16x32_bf16 v[116:119], v[180:183], v[206:209], v[116:119]
	v_mfma_f32_16x16x32_bf16 v[112:115], v[188:191], v[206:209], v[112:115]
	v_mfma_f32_16x16x32_bf16 v[100:103], v[180:183], v[214:217], v[100:103]
	v_mfma_f32_16x16x32_bf16 v[96:99], v[188:191], v[214:217], v[96:99]
	v_mfma_f32_16x16x32_bf16 v[84:87], v[180:183], v[222:225], v[84:87]
	v_mfma_f32_16x16x32_bf16 v[80:83], v[188:191], v[222:225], v[80:83]
	v_mfma_f32_16x16x32_bf16 v[68:71], v[180:183], v[230:233], v[68:71]
	v_mfma_f32_16x16x32_bf16 v[64:67], v[188:191], v[230:233], v[64:67]
	s_setprio 0
	s_barrier
; #define PG8_STAGE(bufoff, gbase, voff) do { _Pragma("unroll") for (int _i = 0; _i < 2; ++_i) \
;         __builtin_amdgcn_global_load_lds((const unsigned*)((const char*)(gbase) + (voff)[_i]), (PG8_LAS unsigned*)(lds + (bufoff) + ldsw + _i * 8192), 16, 0, 0); } while (0)
; #define PG8_LDA(dst, b, h) do { _Pragma("unroll") for (int m = 0; m < 4; ++m) _Pragma("unroll") for (int k = 0; k < 2; ++k) dst[m][k] = *(const PG8_LAS bf16x8*)(lds + PG8_SA(b, h) + aoff + m * 2048 + k * 1024); } while (0)
; #define PG8_MMA(ai, bj, At, Bt) do { __builtin_amdgcn_s_setprio(1); _Pragma("unroll") for (int m = 0; m < 4; ++m) _Pragma("unroll") for (int n = 0; n < 2; ++n) _Pragma("unroll") for (int k = 0; k < 2; ++k) \
;         acc[ai][bj][m][n] = __builtin_amdgcn_mfma_f32_16x16x32_bf16(Bt[n][k], At[m][k], acc[ai][bj][m][n], 0, 0, 0); __builtin_amdgcn_s_setprio(0); } while (0)
; #define PG8_WAIT_V(n) asm volatile("s_waitcnt vmcnt(" #n ")" ::: "memory")
; #define PG8_WAIT_L(n) asm volatile("s_waitcnt lgkmcnt(" #n ")" ::: "memory")
; #define PG8_BAR __builtin_amdgcn_s_barrier()
; #define PG8_SCHED __builtin_amdgcn_sched_barrier(0)
; template <class Epi, class Sched, bool ALIGN_EPI = false, bool SP2 = false>
; __device__ __forceinline__ void gemm_phase(PG8_LAS unsigned char* lds, const Gemm g, const Sched& S, const Epi& E) {
;     ...
;             PG8_LDA(At, 1, 1); PG8_STAGE(PG8_SB(1, 0), b3, voffB); PG8_STAGE(PG8_SB(1, 1), b3 + hstep, voffB); PG8_STAGE(PG8_SA(1, 0), a3, voffA);
;             PG8_WAIT_V(8); PG8_WAIT_L(0); PG8_BAR; PG8_MMA(1, 0, At, B0); PG8_MMA(1, 1, At, B1); PG8_BAR; PG8_SCHED;
	s_add_i32 s30, s52, s34
	v_lshl_add_u64 v[144:145], v[144:145], 0, s[10:11]
	s_mov_b32 m0, s30
	ds_read_b128 v[202:205], v152 offset:49152
	ds_read_b128 v[206:209], v152 offset:50176
	ds_read_b128 v[210:213], v152 offset:51200
	ds_read_b128 v[214:217], v152 offset:52224
	ds_read_b128 v[218:221], v152 offset:53248
	ds_read_b128 v[222:225], v152 offset:54272
	ds_read_b128 v[226:229], v152 offset:55296
	ds_read_b128 v[230:233], v152 offset:56320
	global_load_lds_dwordx4 v[144:145], off
	s_add_i32 m0, s30, 0x2000
	s_add_u32 s28, s28, 0x40080
	v_lshl_add_u64 v[144:145], v[166:167], 0, s[10:11]
	s_addc_u32 s29, s29, 0
	s_add_i32 s30, s53, s34
	global_load_lds_dwordx4 v[144:145], off
	v_lshl_add_u64 v[144:145], s[28:29], 0, v[132:133]
	s_mov_b32 m0, s30
	s_nop 0
	global_load_lds_dwordx4 v[144:145], off
	v_lshl_add_u64 v[144:145], s[28:29], 0, v[128:129]
	s_add_i32 m0, s30, 0x2000
	s_nop 0
	global_load_lds_dwordx4 v[144:145], off
	v_lshl_add_u64 v[144:145], v[192:193], 0, s[10:11]
	s_mov_b32 m0, s41
	s_nop 0
	global_load_lds_dwordx4 v[144:145], off
	v_lshl_add_u64 v[144:145], v[196:197], 0, s[10:11]
	s_mov_b32 m0, s42
	s_nop 0
	global_load_lds_dwordx4 v[144:145], off
	s_waitcnt vmcnt(8)
	s_waitcnt lgkmcnt(0)
	s_barrier
	s_setprio 1
	s_waitcnt lgkmcnt(0)
	v_mfma_f32_16x16x32_bf16 v[60:63], v[154:157], v[202:205], v[60:63]
	v_mfma_f32_16x16x32_bf16 v[56:59], v[162:165], v[202:205], v[56:59]
	v_mfma_f32_16x16x32_bf16 v[44:47], v[154:157], v[210:213], v[44:47]
	v_mfma_f32_16x16x32_bf16 v[40:43], v[162:165], v[210:213], v[40:43]
	v_mfma_f32_16x16x32_bf16 v[28:31], v[154:157], v[218:221], v[28:31]
	v_mfma_f32_16x16x32_bf16 v[24:27], v[162:165], v[218:221], v[24:27]
	v_mfma_f32_16x16x32_bf16 v[12:15], v[154:157], v[226:229], v[12:15]
	v_mfma_f32_16x16x32_bf16 v[8:11], v[162:165], v[226:229], v[8:11]
	v_mfma_f32_16x16x32_bf16 v[60:63], v[158:161], v[206:209], v[60:63]
	v_mfma_f32_16x16x32_bf16 v[56:59], v[172:175], v[206:209], v[56:59]
	v_mfma_f32_16x16x32_bf16 v[44:47], v[158:161], v[214:217], v[44:47]
	v_mfma_f32_16x16x32_bf16 v[40:43], v[172:175], v[214:217], v[40:43]
	v_mfma_f32_16x16x32_bf16 v[28:31], v[158:161], v[222:225], v[28:31]
	v_mfma_f32_16x16x32_bf16 v[24:27], v[172:175], v[222:225], v[24:27]
	v_mfma_f32_16x16x32_bf16 v[12:15], v[158:161], v[230:233], v[12:15]
	v_mfma_f32_16x16x32_bf16 v[8:11], v[172:175], v[230:233], v[8:11]
	s_setprio 0
	s_setprio 1
	v_mfma_f32_16x16x32_bf16 v[52:55], v[176:179], v[202:205], v[52:55]
	s_add_i32 s51, s51, 2
	s_add_u32 s0, s0, 0x100
	s_addc_u32 s1, s1, 0
	s_add_u32 s49, s49, 0x100
	s_addc_u32 s50, s50, 0
	v_mfma_f32_16x16x32_bf16 v[48:51], v[184:187], v[202:205], v[48:51]
	v_mfma_f32_16x16x32_bf16 v[36:39], v[176:179], v[210:213], v[36:39]
	v_mfma_f32_16x16x32_bf16 v[32:35], v[184:187], v[210:213], v[32:35]
	v_mfma_f32_16x16x32_bf16 v[20:23], v[176:179], v[218:221], v[20:23]
	v_mfma_f32_16x16x32_bf16 v[16:19], v[184:187], v[218:221], v[16:19]
	v_mfma_f32_16x16x32_bf16 v[4:7], v[176:179], v[226:229], v[4:7]
	v_mfma_f32_16x16x32_bf16 v[0:3], v[184:187], v[226:229], v[0:3]
	v_mfma_f32_16x16x32_bf16 v[52:55], v[180:183], v[206:209], v[52:55]
	v_mfma_f32_16x16x32_bf16 v[48:51], v[188:191], v[206:209], v[48:51]
	v_mfma_f32_16x16x32_bf16 v[36:39], v[180:183], v[214:217], v[36:39]
	v_mfma_f32_16x16x32_bf16 v[32:35], v[188:191], v[214:217], v[32:35]
	v_mfma_f32_16x16x32_bf16 v[20:23], v[180:183], v[222:225], v[20:23]
	v_mfma_f32_16x16x32_bf16 v[16:19], v[188:191], v[222:225], v[16:19]
	v_mfma_f32_16x16x32_bf16 v[4:7], v[180:183], v[230:233], v[4:7]
	v_mfma_f32_16x16x32_bf16 v[0:3], v[188:191], v[230:233], v[0:3]
	s_setprio 0
	s_barrier
	s_cmp_gt_u32 s51, 13
	s_cbranch_scc0 .LBB0_150
	s_and_b64 vcc, exec, s[12:13]
	s_cbranch_vccz .LBB0_153
	s_barrier

; #define PG8_STAGE(bufoff, gbase, voff) do { _Pragma("unroll") for (int _i = 0; _i < 2; ++_i) \
;         __builtin_amdgcn_global_load_lds((const unsigned*)((const char*)(gbase) + (voff)[_i]), (PG8_LAS unsigned*)(lds + (bufoff) + ldsw + _i * 8192), 16, 0, 0); } while (0)
; #define PG8_LDA(dst, b, h) do { _Pragma("unroll") for (int m = 0; m < 4; ++m) _Pragma("unroll") for (int k = 0; k < 2; ++k) dst[m][k] = *(const PG8_LAS bf16x8*)(lds + PG8_SA(b, h) + aoff + m * 2048 + k * 1024); } while (0)
; #define PG8_LDB(dst, b, h) do { _Pragma("unroll") for (int n = 0; n < 2; ++n) _Pragma("unroll") for (int k = 0; k < 2; ++k) dst[n][k] = *(const PG8_LAS bf16x8*)(lds + PG8_SB(b, h) + boff + n * 2048 + k * 1024); } while (0)
; #define PG8_MMA(ai, bj, At, Bt) do { __builtin_amdgcn_s_setprio(1); _Pragma("unroll") for (int m = 0; m < 4; ++m) _Pragma("unroll") for (int n = 0; n < 2; ++n) _Pragma("unroll") for (int k = 0; k < 2; ++k) \
;         acc[ai][bj][m][n] = __builtin_amdgcn_mfma_f32_16x16x32_bf16(Bt[n][k], At[m][k], acc[ai][bj][m][n], 0, 0, 0); __builtin_amdgcn_s_setprio(0); } while (0)
; #define PG8_WAIT_V(n) asm volatile("s_waitcnt vmcnt(" #n ")" ::: "memory")
; #define PG8_WAIT_L(n) asm volatile("s_waitcnt lgkmcnt(" #n ")" ::: "memory")
; #define PG8_BAR __builtin_amdgcn_s_barrier()
; #define PG8_SCHED __builtin_amdgcn_sched_barrier(0)
; template <class Epi, class Sched, bool ALIGN_EPI = false, bool SP2 = false>
; __device__ __forceinline__ void gemm_phase(PG8_LAS unsigned char* lds, const Gemm g, const Sched& S, const Epi& E) {
;     ...
;             PG8_LDB(B0, 0, 0); PG8_LDB(B1, 0, 1); PG8_SCHED; PG8_LDA(At, 0, 0); PG8_STAGE(PG8_SA(1, 1), a1 + hstep, voffA);
;             PG8_WAIT_V(8); PG8_WAIT_L(0); PG8_BAR; PG8_MMA(0, 0, At, B0); PG8_MMA(0, 1, At, B1); PG8_BAR; PG8_SCHED;
;             PG8_LDA(At, 0, 1); PG8_STAGE(PG8_SB(0, 0), b2, voffB); PG8_STAGE(PG8_SB(0, 1), b2 + hstep, voffB); PG8_STAGE(PG8_SA(0, 0), a2, voffA);
;             PG8_WAIT_V(8); PG8_WAIT_L(0); PG8_BAR; PG8_MMA(1, 0, At, B0); PG8_MMA(1, 1, At, B1); PG8_BAR; PG8_SCHED;
.LBB0_232:
	ds_read_b128 v[128:131], v218
	ds_read_b128 v[132:135], v218 offset:1024
	ds_read_b128 v[136:139], v218 offset:2048
	ds_read_b128 v[140:143], v218 offset:3072
	ds_read_b128 v[144:147], v219
	ds_read_b128 v[148:151], v219 offset:1024
	ds_read_b128 v[152:155], v219 offset:2048
	ds_read_b128 v[156:159], v219 offset:3072
	s_add_u32 s30, s0, 0x100
	s_addc_u32 s31, s1, 0
	s_cmp_eq_u32 s55, 40
	s_cselect_b32 s37, s13, s31
	s_cselect_b32 s36, s12, s30
	s_cselect_b32 s35, s29, s54
	s_cselect_b32 s34, s28, s33
	v_lshl_add_u64 v[192:193], s[0:1], 0, v[182:183]
	s_add_i32 m0, s39, 0xc000
	ds_read_b128 v[160:163], v220
	ds_read_b128 v[164:167], v220 offset:1024
	ds_read_b128 v[188:191], v220 offset:2048
	ds_read_b128 v[226:229], v220 offset:3072
	ds_read_b128 v[230:233], v220 offset:4096
	ds_read_b128 v[234:237], v220 offset:5120
	ds_read_b128 v[238:241], v220 offset:6144
	ds_read_b128 v[242:245], v220 offset:7168
	global_load_lds_dwordx4 v[192:193], off
	v_lshl_add_u64 v[192:193], s[0:1], 0, v[184:185]
	s_add_i32 m0, s39, 0xe000
	s_nop 0
	global_load_lds_dwordx4 v[192:193], off
	s_waitcnt vmcnt(8)
	s_waitcnt lgkmcnt(0)
	s_barrier
	s_setprio 1
	s_waitcnt lgkmcnt(0)
	v_mfma_f32_16x16x32_bf16 v[124:127], v[128:131], v[160:163], v[124:127]
	v_mfma_f32_16x16x32_bf16 v[120:123], v[136:139], v[160:163], v[120:123]
	v_mfma_f32_16x16x32_bf16 v[108:111], v[128:131], v[188:191], v[108:111]
	v_mfma_f32_16x16x32_bf16 v[104:107], v[136:139], v[188:191], v[104:107]
	v_mfma_f32_16x16x32_bf16 v[92:95], v[128:131], v[230:233], v[92:95]
	v_mfma_f32_16x16x32_bf16 v[88:91], v[136:139], v[230:233], v[88:91]
	v_mfma_f32_16x16x32_bf16 v[76:79], v[128:131], v[238:241], v[76:79]
	v_mfma_f32_16x16x32_bf16 v[72:75], v[136:139], v[238:241], v[72:75]
	v_mfma_f32_16x16x32_bf16 v[124:127], v[132:135], v[164:167], v[124:127]
	v_mfma_f32_16x16x32_bf16 v[120:123], v[140:143], v[164:167], v[120:123]
	v_mfma_f32_16x16x32_bf16 v[108:111], v[132:135], v[226:229], v[108:111]
	v_mfma_f32_16x16x32_bf16 v[104:107], v[140:143], v[226:229], v[104:107]
	v_mfma_f32_16x16x32_bf16 v[92:95], v[132:135], v[234:237], v[92:95]
	v_mfma_f32_16x16x32_bf16 v[88:91], v[140:143], v[234:237], v[88:91]
	v_mfma_f32_16x16x32_bf16 v[76:79], v[132:135], v[242:245], v[76:79]
	v_mfma_f32_16x16x32_bf16 v[72:75], v[140:143], v[242:245], v[72:75]
	s_setprio 0
	s_setprio 1
	v_mfma_f32_16x16x32_bf16 v[116:119], v[144:147], v[160:163], v[116:119]
	v_mfma_f32_16x16x32_bf16 v[112:115], v[152:155], v[160:163], v[112:115]
	v_mfma_f32_16x16x32_bf16 v[100:103], v[144:147], v[188:191], v[100:103]
	v_mfma_f32_16x16x32_bf16 v[96:99], v[152:155], v[188:191], v[96:99]
	v_mfma_f32_16x16x32_bf16 v[84:87], v[144:147], v[230:233], v[84:87]
	v_mfma_f32_16x16x32_bf16 v[80:83], v[152:155], v[230:233], v[80:83]
	v_mfma_f32_16x16x32_bf16 v[68:71], v[144:147], v[238:241], v[68:71]
	v_mfma_f32_16x16x32_bf16 v[64:67], v[152:155], v[238:241], v[64:67]
	v_mfma_f32_16x16x32_bf16 v[116:119], v[148:151], v[164:167], v[116:119]
	v_mfma_f32_16x16x32_bf16 v[112:115], v[156:159], v[164:167], v[112:115]
	v_mfma_f32_16x16x32_bf16 v[100:103], v[148:151], v[226:229], v[100:103]
	v_mfma_f32_16x16x32_bf16 v[96:99], v[156:159], v[226:229], v[96:99]
	v_mfma_f32_16x16x32_bf16 v[84:87], v[148:151], v[234:237], v[84:87]
	v_mfma_f32_16x16x32_bf16 v[80:83], v[156:159], v[234:237], v[80:83]
	v_mfma_f32_16x16x32_bf16 v[68:71], v[148:151], v[242:245], v[68:71]
	v_mfma_f32_16x16x32_bf16 v[64:67], v[156:159], v[242:245], v[64:67]
	s_setprio 0
	s_barrier
	s_add_i32 s0, s48, s38
	v_lshl_add_u64 v[192:193], s[34:35], 0, v[174:175]
	s_mov_b32 m0, s0
	ds_read_b128 v[160:163], v220 offset:16384
	ds_read_b128 v[164:167], v220 offset:17408
	ds_read_b128 v[188:191], v220 offset:18432
	ds_read_b128 v[226:229], v220 offset:19456
	ds_read_b128 v[230:233], v220 offset:20480
	ds_read_b128 v[234:237], v220 offset:21504
	ds_read_b128 v[238:241], v220 offset:22528
	ds_read_b128 v[242:245], v220 offset:23552
	global_load_lds_dwordx4 v[192:193], off
	s_add_i32 m0, s0, 0x2000
	s_add_u32 s0, s34, 0xb0000
	v_lshl_add_u64 v[246:247], s[34:35], 0, v[178:179]
	s_addc_u32 s1, s35, 0
	s_add_i32 s56, s49, s38
	global_load_lds_dwordx4 v[246:247], off
	v_lshl_add_u64 v[248:249], s[0:1], 0, v[174:175]
	s_mov_b32 m0, s56
	v_lshl_add_u64 v[250:251], s[36:37], 0, v[176:177]
	global_load_lds_dwordx4 v[248:249], off
	v_lshl_add_u64 v[248:249], s[0:1], 0, v[178:179]
	s_add_i32 m0, s56, 0x2000
	s_nop 0
	global_load_lds_dwordx4 v[248:249], off
	v_lshl_add_u64 v[248:249], s[36:37], 0, v[172:173]
	s_mov_b32 m0, s39
	s_nop 0
	global_load_lds_dwordx4 v[248:249], off
	s_mov_b32 m0, s40
	s_nop 0
	global_load_lds_dwordx4 v[250:251], off
	s_waitcnt vmcnt(8)
	s_waitcnt lgkmcnt(0)
	s_barrier
; #define PG8_STAGE(bufoff, gbase, voff) do { _Pragma("unroll") for (int _i = 0; _i < 2; ++_i) \
;         __builtin_amdgcn_global_load_lds((const unsigned*)((const char*)(gbase) + (voff)[_i]), (PG8_LAS unsigned*)(lds + (bufoff) + ldsw + _i * 8192), 16, 0, 0); } while (0)
; #define PG8_LDA(dst, b, h) do { _Pragma("unroll") for (int m = 0; m < 4; ++m) _Pragma("unroll") for (int k = 0; k < 2; ++k) dst[m][k] = *(const PG8_LAS bf16x8*)(lds + PG8_SA(b, h) + aoff + m * 2048 + k * 1024); } while (0)
; #define PG8_LDB(dst, b, h) do { _Pragma("unroll") for (int n = 0; n < 2; ++n) _Pragma("unroll") for (int k = 0; k < 2; ++k) dst[n][k] = *(const PG8_LAS bf16x8*)(lds + PG8_SB(b, h) + boff + n * 2048 + k * 1024); } while (0)
; #define PG8_MMA(ai, bj, At, Bt) do { __builtin_amdgcn_s_setprio(1); _Pragma("unroll") for (int m = 0; m < 4; ++m) _Pragma("unroll") for (int n = 0; n < 2; ++n) _Pragma("unroll") for (int k = 0; k < 2; ++k) \
;         acc[ai][bj][m][n] = __builtin_amdgcn_mfma_f32_16x16x32_bf16(Bt[n][k], At[m][k], acc[ai][bj][m][n], 0, 0, 0); __builtin_amdgcn_s_setprio(0); } while (0)
; #define PG8_WAIT_V(n) asm volatile("s_waitcnt vmcnt(" #n ")" ::: "memory")
; #define PG8_WAIT_L(n) asm volatile("s_waitcnt lgkmcnt(" #n ")" ::: "memory")
; #define PG8_BAR __builtin_amdgcn_s_barrier()
; #define PG8_SCHED __builtin_amdgcn_sched_barrier(0)
; template <class Epi, class Sched, bool ALIGN_EPI = false, bool SP2 = false>
; __device__ __forceinline__ void gemm_phase(PG8_LAS unsigned char* lds, const Gemm g, const Sched& S, const Epi& E) {
;     ...
;             PG8_WAIT_V(8); PG8_WAIT_L(0); PG8_BAR; PG8_MMA(1, 0, At, B0); PG8_MMA(1, 1, At, B1); PG8_BAR; PG8_SCHED;
;             PG8_LDB(B0, 1, 0); PG8_LDB(B1, 1, 1); PG8_SCHED; PG8_LDA(At, 1, 0); PG8_STAGE(PG8_SA(0, 1), a2 + hstep, voffA);
;             PG8_WAIT_V(8); PG8_WAIT_L(0); PG8_BAR; PG8_MMA(0, 0, At, B0); PG8_MMA(0, 1, At, B1); PG8_BAR; PG8_SCHED;
	s_setprio 1
	s_waitcnt lgkmcnt(0)
	v_mfma_f32_16x16x32_bf16 v[60:63], v[128:131], v[160:163], v[60:63]
	v_mfma_f32_16x16x32_bf16 v[56:59], v[136:139], v[160:163], v[56:59]
	v_mfma_f32_16x16x32_bf16 v[44:47], v[128:131], v[188:191], v[44:47]
	v_mfma_f32_16x16x32_bf16 v[40:43], v[136:139], v[188:191], v[40:43]
	v_mfma_f32_16x16x32_bf16 v[28:31], v[128:131], v[230:233], v[28:31]
	v_mfma_f32_16x16x32_bf16 v[24:27], v[136:139], v[230:233], v[24:27]
	v_mfma_f32_16x16x32_bf16 v[12:15], v[128:131], v[238:241], v[12:15]
	v_mfma_f32_16x16x32_bf16 v[8:11], v[136:139], v[238:241], v[8:11]
	v_mfma_f32_16x16x32_bf16 v[60:63], v[132:135], v[164:167], v[60:63]
	v_mfma_f32_16x16x32_bf16 v[56:59], v[140:143], v[164:167], v[56:59]
	v_mfma_f32_16x16x32_bf16 v[44:47], v[132:135], v[226:229], v[44:47]
	v_mfma_f32_16x16x32_bf16 v[40:43], v[140:143], v[226:229], v[40:43]
	v_mfma_f32_16x16x32_bf16 v[28:31], v[132:135], v[234:237], v[28:31]
	v_mfma_f32_16x16x32_bf16 v[24:27], v[140:143], v[234:237], v[24:27]
	v_mfma_f32_16x16x32_bf16 v[12:15], v[132:135], v[242:245], v[12:15]
	v_mfma_f32_16x16x32_bf16 v[8:11], v[140:143], v[242:245], v[8:11]
	s_setprio 0
	s_setprio 1
	v_mfma_f32_16x16x32_bf16 v[52:55], v[144:147], v[160:163], v[52:55]
	v_mfma_f32_16x16x32_bf16 v[48:51], v[152:155], v[160:163], v[48:51]
	v_mfma_f32_16x16x32_bf16 v[36:39], v[144:147], v[188:191], v[36:39]
	v_mfma_f32_16x16x32_bf16 v[32:35], v[152:155], v[188:191], v[32:35]
	v_mfma_f32_16x16x32_bf16 v[20:23], v[144:147], v[230:233], v[20:23]
	v_mfma_f32_16x16x32_bf16 v[16:19], v[152:155], v[230:233], v[16:19]
	v_mfma_f32_16x16x32_bf16 v[4:7], v[144:147], v[238:241], v[4:7]
	v_mfma_f32_16x16x32_bf16 v[0:3], v[152:155], v[238:241], v[0:3]
	v_mfma_f32_16x16x32_bf16 v[52:55], v[148:151], v[164:167], v[52:55]
	v_mfma_f32_16x16x32_bf16 v[48:51], v[156:159], v[164:167], v[48:51]
	v_mfma_f32_16x16x32_bf16 v[36:39], v[148:151], v[226:229], v[36:39]
	v_mfma_f32_16x16x32_bf16 v[32:35], v[156:159], v[226:229], v[32:35]
	v_mfma_f32_16x16x32_bf16 v[20:23], v[148:151], v[234:237], v[20:23]
	v_mfma_f32_16x16x32_bf16 v[16:19], v[156:159], v[234:237], v[16:19]
	v_mfma_f32_16x16x32_bf16 v[4:7], v[148:151], v[242:245], v[4:7]
	v_mfma_f32_16x16x32_bf16 v[0:3], v[156:159], v[242:245], v[0:3]
	s_setprio 0
	s_barrier
	s_add_i32 s56, 0, 0x18000
	s_add_i32 s57, 0, 0x1c000
	v_add_u32_e32 v140, s56, v196
	v_add_u32_e32 v156, s57, v196
	ds_read_b128 v[128:131], v140
	ds_read_b128 v[132:135], v140 offset:1024
	ds_read_b128 v[136:139], v140 offset:2048
	ds_read_b128 v[140:143], v140 offset:3072
	ds_read_b128 v[144:147], v156
	ds_read_b128 v[148:151], v156 offset:1024
	ds_read_b128 v[152:155], v156 offset:2048
	ds_read_b128 v[156:159], v156 offset:3072
	s_add_u32 s0, s36, 0xb0000
	s_addc_u32 s1, s37, 0
	s_mov_b32 m0, s41
	v_lshl_add_u64 v[252:253], s[0:1], 0, v[172:173]
	ds_read_b128 v[160:163], v220 offset:32768
	ds_read_b128 v[164:167], v220 offset:33792
	ds_read_b128 v[188:191], v220 offset:34816
	ds_read_b128 v[226:229], v220 offset:35840
	ds_read_b128 v[230:233], v220 offset:36864
	ds_read_b128 v[234:237], v220 offset:37888
	ds_read_b128 v[238:241], v220 offset:38912
	ds_read_b128 v[242:245], v220 offset:39936
	global_load_lds_dwordx4 v[252:253], off
	v_lshl_add_u64 v[252:253], s[0:1], 0, v[176:177]
	s_mov_b32 m0, s42
	s_nop 0
	global_load_lds_dwordx4 v[252:253], off
	s_waitcnt vmcnt(8)
	s_waitcnt lgkmcnt(0)
	s_barrier
	s_setprio 1
	s_waitcnt lgkmcnt(0)
	v_mfma_f32_16x16x32_bf16 v[124:127], v[128:131], v[160:163], v[124:127]
	v_mfma_f32_16x16x32_bf16 v[120:123], v[136:139], v[160:163], v[120:123]
	v_mfma_f32_16x16x32_bf16 v[108:111], v[128:131], v[188:191], v[108:111]
	v_mfma_f32_16x16x32_bf16 v[104:107], v[136:139], v[188:191], v[104:107]
	v_mfma_f32_16x16x32_bf16 v[92:95], v[128:131], v[230:233], v[92:95]
	v_mfma_f32_16x16x32_bf16 v[88:91], v[136:139], v[230:233], v[88:91]
	v_mfma_f32_16x16x32_bf16 v[76:79], v[128:131], v[238:241], v[76:79]
	v_mfma_f32_16x16x32_bf16 v[72:75], v[136:139], v[238:241], v[72:75]
	v_mfma_f32_16x16x32_bf16 v[124:127], v[132:135], v[164:167], v[124:127]
	v_mfma_f32_16x16x32_bf16 v[120:123], v[140:143], v[164:167], v[120:123]
	v_mfma_f32_16x16x32_bf16 v[108:111], v[132:135], v[226:229], v[108:111]
	v_mfma_f32_16x16x32_bf16 v[104:107], v[140:143], v[226:229], v[104:107]
	v_mfma_f32_16x16x32_bf16 v[92:95], v[132:135], v[234:237], v[92:95]
	v_mfma_f32_16x16x32_bf16 v[88:91], v[140:143], v[234:237], v[88:91]
	v_mfma_f32_16x16x32_bf16 v[76:79], v[132:135], v[242:245], v[76:79]
	v_mfma_f32_16x16x32_bf16 v[72:75], v[140:143], v[242:245], v[72:75]
	s_setprio 0
	s_setprio 1
	v_mfma_f32_16x16x32_bf16 v[116:119], v[144:147], v[160:163], v[116:119]
	v_mfma_f32_16x16x32_bf16 v[112:115], v[152:155], v[160:163], v[112:115]
	v_mfma_f32_16x16x32_bf16 v[100:103], v[144:147], v[188:191], v[100:103]
	v_mfma_f32_16x16x32_bf16 v[96:99], v[152:155], v[188:191], v[96:99]
	v_mfma_f32_16x16x32_bf16 v[84:87], v[144:147], v[230:233], v[84:87]
	v_mfma_f32_16x16x32_bf16 v[80:83], v[152:155], v[230:233], v[80:83]
	v_mfma_f32_16x16x32_bf16 v[68:71], v[144:147], v[238:241], v[68:71]
	v_mfma_f32_16x16x32_bf16 v[64:67], v[152:155], v[238:241], v[64:67]
	v_mfma_f32_16x16x32_bf16 v[116:119], v[148:151], v[164:167], v[116:119]
	v_mfma_f32_16x16x32_bf16 v[112:115], v[156:159], v[164:167], v[112:115]
	v_mfma_f32_16x16x32_bf16 v[100:103], v[148:151], v[226:229], v[100:103]
	v_mfma_f32_16x16x32_bf16 v[96:99], v[156:159], v[226:229], v[96:99]
	v_mfma_f32_16x16x32_bf16 v[84:87], v[148:151], v[234:237], v[84:87]
	v_mfma_f32_16x16x32_bf16 v[80:83], v[156:159], v[234:237], v[80:83]
	v_mfma_f32_16x16x32_bf16 v[68:71], v[148:151], v[242:245], v[68:71]
	v_mfma_f32_16x16x32_bf16 v[64:67], v[156:159], v[242:245], v[64:67]
	s_setprio 0
	s_barrier
; #define PG8_STAGE(bufoff, gbase, voff) do { _Pragma("unroll") for (int _i = 0; _i < 2; ++_i) \
;         __builtin_amdgcn_global_load_lds((const unsigned*)((const char*)(gbase) + (voff)[_i]), (PG8_LAS unsigned*)(lds + (bufoff) + ldsw + _i * 8192), 16, 0, 0); } while (0)
; #define PG8_LDA(dst, b, h) do { _Pragma("unroll") for (int m = 0; m < 4; ++m) _Pragma("unroll") for (int k = 0; k < 2; ++k) dst[m][k] = *(const PG8_LAS bf16x8*)(lds + PG8_SA(b, h) + aoff + m * 2048 + k * 1024); } while (0)
; #define PG8_MMA(ai, bj, At, Bt) do { __builtin_amdgcn_s_setprio(1); _Pragma("unroll") for (int m = 0; m < 4; ++m) _Pragma("unroll") for (int n = 0; n < 2; ++n) _Pragma("unroll") for (int k = 0; k < 2; ++k) \
;         acc[ai][bj][m][n] = __builtin_amdgcn_mfma_f32_16x16x32_bf16(Bt[n][k], At[m][k], acc[ai][bj][m][n], 0, 0, 0); __builtin_amdgcn_s_setprio(0); } while (0)
; #define PG8_WAIT_V(n) asm volatile("s_waitcnt vmcnt(" #n ")" ::: "memory")
; #define PG8_WAIT_L(n) asm volatile("s_waitcnt lgkmcnt(" #n ")" ::: "memory")
; #define PG8_BAR __builtin_amdgcn_s_barrier()
; #define PG8_SCHED __builtin_amdgcn_sched_barrier(0)
; template <class Epi, class Sched, bool ALIGN_EPI = false, bool SP2 = false>
; __device__ __forceinline__ void gemm_phase(PG8_LAS unsigned char* lds, const Gemm g, const Sched& S, const Epi& E) {
;     ...
;             PG8_LDA(At, 1, 1); PG8_STAGE(PG8_SB(1, 0), b3, voffB); PG8_STAGE(PG8_SB(1, 1), b3 + hstep, voffB); PG8_STAGE(PG8_SA(1, 0), a3, voffA);
;             PG8_WAIT_V(8); PG8_WAIT_L(0); PG8_BAR; PG8_MMA(1, 0, At, B0); PG8_MMA(1, 1, At, B1); PG8_BAR; PG8_SCHED;
	s_add_i32 s0, s56, s38
	v_lshl_add_u64 v[192:193], v[192:193], 0, s[22:23]
	s_mov_b32 m0, s0
	ds_read_b128 v[160:163], v220 offset:49152
	ds_read_b128 v[164:167], v220 offset:50176
	ds_read_b128 v[188:191], v220 offset:51200
	ds_read_b128 v[226:229], v220 offset:52224
	ds_read_b128 v[230:233], v220 offset:53248
	ds_read_b128 v[234:237], v220 offset:54272
	ds_read_b128 v[238:241], v220 offset:55296
	ds_read_b128 v[242:245], v220 offset:56320
	global_load_lds_dwordx4 v[192:193], off
	s_add_i32 m0, s0, 0x2000
	s_add_u32 s0, s34, 0xb0080
	v_lshl_add_u64 v[192:193], v[246:247], 0, s[22:23]
	s_addc_u32 s1, s35, 0
	s_add_i32 s34, s57, s38
	global_load_lds_dwordx4 v[192:193], off
	v_lshl_add_u64 v[192:193], s[0:1], 0, v[174:175]
	s_mov_b32 m0, s34
	s_nop 0
	global_load_lds_dwordx4 v[192:193], off
	v_lshl_add_u64 v[192:193], s[0:1], 0, v[178:179]
	s_add_i32 m0, s34, 0x2000
	s_nop 0
	global_load_lds_dwordx4 v[192:193], off
	v_lshl_add_u64 v[192:193], v[248:249], 0, s[22:23]
	s_mov_b32 m0, s44
	s_nop 0
	global_load_lds_dwordx4 v[192:193], off
	v_lshl_add_u64 v[192:193], v[250:251], 0, s[22:23]
	s_mov_b32 m0, s45
	s_nop 0
	global_load_lds_dwordx4 v[192:193], off
	s_waitcnt vmcnt(8)
	s_waitcnt lgkmcnt(0)
	s_barrier
	s_setprio 1
	s_waitcnt lgkmcnt(0)
	v_mfma_f32_16x16x32_bf16 v[60:63], v[128:131], v[160:163], v[60:63]
	v_mfma_f32_16x16x32_bf16 v[56:59], v[136:139], v[160:163], v[56:59]
	v_mfma_f32_16x16x32_bf16 v[44:47], v[128:131], v[188:191], v[44:47]
	v_mfma_f32_16x16x32_bf16 v[40:43], v[136:139], v[188:191], v[40:43]
	v_mfma_f32_16x16x32_bf16 v[28:31], v[128:131], v[230:233], v[28:31]
	v_mfma_f32_16x16x32_bf16 v[24:27], v[136:139], v[230:233], v[24:27]
	v_mfma_f32_16x16x32_bf16 v[12:15], v[128:131], v[238:241], v[12:15]
	v_mfma_f32_16x16x32_bf16 v[8:11], v[136:139], v[238:241], v[8:11]
	v_mfma_f32_16x16x32_bf16 v[60:63], v[132:135], v[164:167], v[60:63]
	v_mfma_f32_16x16x32_bf16 v[56:59], v[140:143], v[164:167], v[56:59]
	v_mfma_f32_16x16x32_bf16 v[44:47], v[132:135], v[226:229], v[44:47]
	v_mfma_f32_16x16x32_bf16 v[40:43], v[140:143], v[226:229], v[40:43]
	v_mfma_f32_16x16x32_bf16 v[28:31], v[132:135], v[234:237], v[28:31]
	v_mfma_f32_16x16x32_bf16 v[24:27], v[140:143], v[234:237], v[24:27]
	v_mfma_f32_16x16x32_bf16 v[12:15], v[132:135], v[242:245], v[12:15]
	v_mfma_f32_16x16x32_bf16 v[8:11], v[140:143], v[242:245], v[8:11]
	s_setprio 0
	s_setprio 1
	v_mfma_f32_16x16x32_bf16 v[52:55], v[144:147], v[160:163], v[52:55]
	s_add_i32 s55, s55, 2
	s_add_u32 s33, s33, 0x100
	s_addc_u32 s54, s54, 0
	v_mfma_f32_16x16x32_bf16 v[48:51], v[152:155], v[160:163], v[48:51]
	v_mfma_f32_16x16x32_bf16 v[36:39], v[144:147], v[188:191], v[36:39]
	v_mfma_f32_16x16x32_bf16 v[32:35], v[152:155], v[188:191], v[32:35]
	v_mfma_f32_16x16x32_bf16 v[20:23], v[144:147], v[230:233], v[20:23]
	v_mfma_f32_16x16x32_bf16 v[16:19], v[152:155], v[230:233], v[16:19]
	v_mfma_f32_16x16x32_bf16 v[4:7], v[144:147], v[238:241], v[4:7]
	v_mfma_f32_16x16x32_bf16 v[0:3], v[152:155], v[238:241], v[0:3]
	v_mfma_f32_16x16x32_bf16 v[52:55], v[148:151], v[164:167], v[52:55]
	v_mfma_f32_16x16x32_bf16 v[48:51], v[156:159], v[164:167], v[48:51]
	v_mfma_f32_16x16x32_bf16 v[36:39], v[148:151], v[226:229], v[36:39]
	v_mfma_f32_16x16x32_bf16 v[32:35], v[156:159], v[226:229], v[32:35]
	v_mfma_f32_16x16x32_bf16 v[20:23], v[148:151], v[234:237], v[20:23]
	v_mfma_f32_16x16x32_bf16 v[16:19], v[156:159], v[234:237], v[16:19]
	v_mfma_f32_16x16x32_bf16 v[4:7], v[148:151], v[242:245], v[4:7]
	v_mfma_f32_16x16x32_bf16 v[0:3], v[156:159], v[242:245], v[0:3]
	s_setprio 0
	s_barrier
	s_cmp_gt_u32 s55, 41
	s_mov_b64 s[0:1], s[30:31]
	s_cbranch_scc0 .LBB0_232
	s_and_b64 vcc, exec, s[24:25]
	s_cbranch_vccz .LBB0_235
	s_barrier

; #define PG8_STAGE(bufoff, gbase, voff) do { _Pragma("unroll") for (int _i = 0; _i < 2; ++_i) \
;         __builtin_amdgcn_global_load_lds((const unsigned*)((const char*)(gbase) + (voff)[_i]), (PG8_LAS unsigned*)(lds + (bufoff) + ldsw + _i * 8192), 16, 0, 0); } while (0)
; #define PG8_LDA(dst, b, h) do { _Pragma("unroll") for (int m = 0; m < 4; ++m) _Pragma("unroll") for (int k = 0; k < 2; ++k) dst[m][k] = *(const PG8_LAS bf16x8*)(lds + PG8_SA(b, h) + aoff + m * 2048 + k * 1024); } while (0)
; #define PG8_LDB(dst, b, h) do { _Pragma("unroll") for (int n = 0; n < 2; ++n) _Pragma("unroll") for (int k = 0; k < 2; ++k) dst[n][k] = *(const PG8_LAS bf16x8*)(lds + PG8_SB(b, h) + boff + n * 2048 + k * 1024); } while (0)
; #define PG8_MMA(ai, bj, At, Bt) do { __builtin_amdgcn_s_setprio(1); _Pragma("unroll") for (int m = 0; m < 4; ++m) _Pragma("unroll") for (int n = 0; n < 2; ++n) _Pragma("unroll") for (int k = 0; k < 2; ++k) \
;         acc[ai][bj][m][n] = __builtin_amdgcn_mfma_f32_16x16x32_bf16(Bt[n][k], At[m][k], acc[ai][bj][m][n], 0, 0, 0); __builtin_amdgcn_s_setprio(0); } while (0)
; #define PG8_WAIT_V(n) asm volatile("s_waitcnt vmcnt(" #n ")" ::: "memory")
; #define PG8_WAIT_L(n) asm volatile("s_waitcnt lgkmcnt(" #n ")" ::: "memory")
; #define PG8_BAR __builtin_amdgcn_s_barrier()
; #define PG8_SCHED __builtin_amdgcn_sched_barrier(0)
; template <class Epi, class Sched, bool ALIGN_EPI = false, bool SP2 = false>
; __device__ __forceinline__ void gemm_phase(PG8_LAS unsigned char* lds, const Gemm g, const Sched& S, const Epi& E) {
;     ...
;             PG8_LDB(B0, 0, 0); PG8_LDB(B1, 0, 1); PG8_SCHED; PG8_LDA(At, 0, 0); PG8_STAGE(PG8_SA(1, 1), a1 + hstep, voffA);
;             PG8_WAIT_V(8); PG8_WAIT_L(0); PG8_BAR; PG8_MMA(0, 0, At, B0); PG8_MMA(0, 1, At, B1); PG8_BAR; PG8_SCHED;
;             PG8_LDA(At, 0, 1); PG8_STAGE(PG8_SB(0, 0), b2, voffB); PG8_STAGE(PG8_SB(0, 1), b2 + hstep, voffB); PG8_STAGE(PG8_SA(0, 0), a2, voffA);
;             PG8_WAIT_V(8); PG8_WAIT_L(0); PG8_BAR; PG8_MMA(1, 0, At, B0); PG8_MMA(1, 1, At, B1); PG8_BAR; PG8_SCHED;
.LBB0_369:
	ds_read_b128 v[128:131], v169
	ds_read_b128 v[150:153], v169 offset:1024
	ds_read_b128 v[154:157], v169 offset:2048
	ds_read_b128 v[158:161], v169 offset:3072
	ds_read_b128 v[176:179], v172
	ds_read_b128 v[180:183], v172 offset:1024
	ds_read_b128 v[184:187], v172 offset:2048
	ds_read_b128 v[188:191], v172 offset:3072
	s_add_u32 s36, s0, 0xfffc0080
	s_addc_u32 s37, s1, -1
	s_cmp_eq_u32 s53, 12
	s_cselect_b32 s39, s7, s37
	s_cselect_b32 s38, s27, s36
	s_cselect_b32 s37, s25, s52
	s_cselect_b32 s36, s33, s51
	v_lshl_add_u64 v[162:163], s[0:1], 0, v[142:143]
	s_add_i32 m0, s35, 0xc000
	ds_read_b128 v[202:205], v173
	ds_read_b128 v[206:209], v173 offset:1024
	ds_read_b128 v[210:213], v173 offset:2048
	ds_read_b128 v[214:217], v173 offset:3072
	ds_read_b128 v[218:221], v173 offset:4096
	ds_read_b128 v[222:225], v173 offset:5120
	ds_read_b128 v[226:229], v173 offset:6144
	ds_read_b128 v[230:233], v173 offset:7168
	global_load_lds_dwordx4 v[162:163], off
	v_lshl_add_u64 v[162:163], s[0:1], 0, v[144:145]
	s_add_i32 m0, s35, 0xe000
	s_nop 0
	global_load_lds_dwordx4 v[162:163], off
	s_waitcnt vmcnt(8)
	s_waitcnt lgkmcnt(0)
	s_barrier
	s_setprio 1
	s_waitcnt lgkmcnt(0)
	v_mfma_f32_16x16x32_bf16 v[124:127], v[128:131], v[202:205], v[124:127]
	v_mfma_f32_16x16x32_bf16 v[120:123], v[154:157], v[202:205], v[120:123]
	v_mfma_f32_16x16x32_bf16 v[108:111], v[128:131], v[210:213], v[108:111]
	v_mfma_f32_16x16x32_bf16 v[104:107], v[154:157], v[210:213], v[104:107]
	v_mfma_f32_16x16x32_bf16 v[92:95], v[128:131], v[218:221], v[92:95]
	v_mfma_f32_16x16x32_bf16 v[88:91], v[154:157], v[218:221], v[88:91]
	v_mfma_f32_16x16x32_bf16 v[76:79], v[128:131], v[226:229], v[76:79]
	v_mfma_f32_16x16x32_bf16 v[72:75], v[154:157], v[226:229], v[72:75]
	v_mfma_f32_16x16x32_bf16 v[124:127], v[150:153], v[206:209], v[124:127]
	v_mfma_f32_16x16x32_bf16 v[120:123], v[158:161], v[206:209], v[120:123]
	v_mfma_f32_16x16x32_bf16 v[108:111], v[150:153], v[214:217], v[108:111]
	v_mfma_f32_16x16x32_bf16 v[104:107], v[158:161], v[214:217], v[104:107]
	v_mfma_f32_16x16x32_bf16 v[92:95], v[150:153], v[222:225], v[92:95]
	v_mfma_f32_16x16x32_bf16 v[88:91], v[158:161], v[222:225], v[88:91]
	v_mfma_f32_16x16x32_bf16 v[76:79], v[150:153], v[230:233], v[76:79]
	v_mfma_f32_16x16x32_bf16 v[72:75], v[158:161], v[230:233], v[72:75]
	s_setprio 0
	s_setprio 1
	v_mfma_f32_16x16x32_bf16 v[116:119], v[176:179], v[202:205], v[116:119]
	v_mfma_f32_16x16x32_bf16 v[112:115], v[184:187], v[202:205], v[112:115]
	v_mfma_f32_16x16x32_bf16 v[100:103], v[176:179], v[210:213], v[100:103]
	v_mfma_f32_16x16x32_bf16 v[96:99], v[184:187], v[210:213], v[96:99]
	v_mfma_f32_16x16x32_bf16 v[84:87], v[176:179], v[218:221], v[84:87]
	v_mfma_f32_16x16x32_bf16 v[80:83], v[184:187], v[218:221], v[80:83]
	v_mfma_f32_16x16x32_bf16 v[68:71], v[176:179], v[226:229], v[68:71]
	v_mfma_f32_16x16x32_bf16 v[64:67], v[184:187], v[226:229], v[64:67]
	v_mfma_f32_16x16x32_bf16 v[116:119], v[180:183], v[206:209], v[116:119]
	v_mfma_f32_16x16x32_bf16 v[112:115], v[188:191], v[206:209], v[112:115]
	v_mfma_f32_16x16x32_bf16 v[100:103], v[180:183], v[214:217], v[100:103]
	v_mfma_f32_16x16x32_bf16 v[96:99], v[188:191], v[214:217], v[96:99]
	v_mfma_f32_16x16x32_bf16 v[84:87], v[180:183], v[222:225], v[84:87]
	v_mfma_f32_16x16x32_bf16 v[80:83], v[188:191], v[222:225], v[80:83]
	v_mfma_f32_16x16x32_bf16 v[68:71], v[180:183], v[230:233], v[68:71]
	v_mfma_f32_16x16x32_bf16 v[64:67], v[188:191], v[230:233], v[64:67]
	s_setprio 0
	s_barrier
	s_add_i32 s54, s49, s40
	v_lshl_add_u64 v[162:163], s[36:37], 0, v[134:135]
	s_mov_b32 m0, s54
	ds_read_b128 v[202:205], v173 offset:16384
	ds_read_b128 v[206:209], v173 offset:17408
	ds_read_b128 v[210:213], v173 offset:18432
	ds_read_b128 v[214:217], v173 offset:19456
	ds_read_b128 v[218:221], v173 offset:20480
	ds_read_b128 v[222:225], v173 offset:21504
	ds_read_b128 v[226:229], v173 offset:22528
	ds_read_b128 v[230:233], v173 offset:23552
	global_load_lds_dwordx4 v[162:163], off
	s_add_i32 m0, s54, 0x2000
	s_add_u32 s54, s36, 0x40000
	v_lshl_add_u64 v[192:193], s[36:37], 0, v[138:139]
	s_addc_u32 s55, s37, 0
	s_add_i32 s56, s50, s40
	global_load_lds_dwordx4 v[192:193], off
	v_lshl_add_u64 v[196:197], s[54:55], 0, v[134:135]
	s_mov_b32 m0, s56
	v_lshl_add_u64 v[234:235], s[38:39], 0, v[136:137]
	global_load_lds_dwordx4 v[196:197], off
	v_lshl_add_u64 v[196:197], s[54:55], 0, v[138:139]
	s_add_i32 m0, s56, 0x2000
	s_nop 0
	global_load_lds_dwordx4 v[196:197], off
	v_lshl_add_u64 v[196:197], s[38:39], 0, v[132:133]
	s_mov_b32 m0, s35
	s_nop 0
	global_load_lds_dwordx4 v[196:197], off
	s_mov_b32 m0, s41
	s_nop 0
	global_load_lds_dwordx4 v[234:235], off
	s_waitcnt vmcnt(8)
	s_waitcnt lgkmcnt(0)
	s_barrier
; #define PG8_STAGE(bufoff, gbase, voff) do { _Pragma("unroll") for (int _i = 0; _i < 2; ++_i) \
;         __builtin_amdgcn_global_load_lds((const unsigned*)((const char*)(gbase) + (voff)[_i]), (PG8_LAS unsigned*)(lds + (bufoff) + ldsw + _i * 8192), 16, 0, 0); } while (0)
; #define PG8_LDA(dst, b, h) do { _Pragma("unroll") for (int m = 0; m < 4; ++m) _Pragma("unroll") for (int k = 0; k < 2; ++k) dst[m][k] = *(const PG8_LAS bf16x8*)(lds + PG8_SA(b, h) + aoff + m * 2048 + k * 1024); } while (0)
; #define PG8_LDB(dst, b, h) do { _Pragma("unroll") for (int n = 0; n < 2; ++n) _Pragma("unroll") for (int k = 0; k < 2; ++k) dst[n][k] = *(const PG8_LAS bf16x8*)(lds + PG8_SB(b, h) + boff + n * 2048 + k * 1024); } while (0)
; #define PG8_MMA(ai, bj, At, Bt) do { __builtin_amdgcn_s_setprio(1); _Pragma("unroll") for (int m = 0; m < 4; ++m) _Pragma("unroll") for (int n = 0; n < 2; ++n) _Pragma("unroll") for (int k = 0; k < 2; ++k) \
;         acc[ai][bj][m][n] = __builtin_amdgcn_mfma_f32_16x16x32_bf16(Bt[n][k], At[m][k], acc[ai][bj][m][n], 0, 0, 0); __builtin_amdgcn_s_setprio(0); } while (0)
; #define PG8_WAIT_V(n) asm volatile("s_waitcnt vmcnt(" #n ")" ::: "memory")
; #define PG8_WAIT_L(n) asm volatile("s_waitcnt lgkmcnt(" #n ")" ::: "memory")
; #define PG8_BAR __builtin_amdgcn_s_barrier()
; #define PG8_SCHED __builtin_amdgcn_sched_barrier(0)
; template <class Epi, class Sched, bool ALIGN_EPI = false, bool SP2 = false>
; __device__ __forceinline__ void gemm_phase(PG8_LAS unsigned char* lds, const Gemm g, const Sched& S, const Epi& E) {
;     ...
;             PG8_WAIT_V(8); PG8_WAIT_L(0); PG8_BAR; PG8_MMA(1, 0, At, B0); PG8_MMA(1, 1, At, B1); PG8_BAR; PG8_SCHED;
;             PG8_LDB(B0, 1, 0); PG8_LDB(B1, 1, 1); PG8_SCHED; PG8_LDA(At, 1, 0); PG8_STAGE(PG8_SA(0, 1), a2 + hstep, voffA);
;             PG8_WAIT_V(8); PG8_WAIT_L(0); PG8_BAR; PG8_MMA(0, 0, At, B0); PG8_MMA(0, 1, At, B1); PG8_BAR; PG8_SCHED;
	s_setprio 1
	s_waitcnt lgkmcnt(0)
	v_mfma_f32_16x16x32_bf16 v[60:63], v[128:131], v[202:205], v[60:63]
	v_mfma_f32_16x16x32_bf16 v[56:59], v[154:157], v[202:205], v[56:59]
	v_mfma_f32_16x16x32_bf16 v[44:47], v[128:131], v[210:213], v[44:47]
	v_mfma_f32_16x16x32_bf16 v[40:43], v[154:157], v[210:213], v[40:43]
	v_mfma_f32_16x16x32_bf16 v[28:31], v[128:131], v[218:221], v[28:31]
	v_mfma_f32_16x16x32_bf16 v[24:27], v[154:157], v[218:221], v[24:27]
	v_mfma_f32_16x16x32_bf16 v[12:15], v[128:131], v[226:229], v[12:15]
	v_mfma_f32_16x16x32_bf16 v[8:11], v[154:157], v[226:229], v[8:11]
	v_mfma_f32_16x16x32_bf16 v[60:63], v[150:153], v[206:209], v[60:63]
	v_mfma_f32_16x16x32_bf16 v[56:59], v[158:161], v[206:209], v[56:59]
	v_mfma_f32_16x16x32_bf16 v[44:47], v[150:153], v[214:217], v[44:47]
	v_mfma_f32_16x16x32_bf16 v[40:43], v[158:161], v[214:217], v[40:43]
	v_mfma_f32_16x16x32_bf16 v[28:31], v[150:153], v[222:225], v[28:31]
	v_mfma_f32_16x16x32_bf16 v[24:27], v[158:161], v[222:225], v[24:27]
	v_mfma_f32_16x16x32_bf16 v[12:15], v[150:153], v[230:233], v[12:15]
	v_mfma_f32_16x16x32_bf16 v[8:11], v[158:161], v[230:233], v[8:11]
	s_setprio 0
	s_setprio 1
	v_mfma_f32_16x16x32_bf16 v[52:55], v[176:179], v[202:205], v[52:55]
	v_mfma_f32_16x16x32_bf16 v[48:51], v[184:187], v[202:205], v[48:51]
	v_mfma_f32_16x16x32_bf16 v[36:39], v[176:179], v[210:213], v[36:39]
	v_mfma_f32_16x16x32_bf16 v[32:35], v[184:187], v[210:213], v[32:35]
	v_mfma_f32_16x16x32_bf16 v[20:23], v[176:179], v[218:221], v[20:23]
	v_mfma_f32_16x16x32_bf16 v[16:19], v[184:187], v[218:221], v[16:19]
	v_mfma_f32_16x16x32_bf16 v[4:7], v[176:179], v[226:229], v[4:7]
	v_mfma_f32_16x16x32_bf16 v[0:3], v[184:187], v[226:229], v[0:3]
	v_mfma_f32_16x16x32_bf16 v[52:55], v[180:183], v[206:209], v[52:55]
	v_mfma_f32_16x16x32_bf16 v[48:51], v[188:191], v[206:209], v[48:51]
	v_mfma_f32_16x16x32_bf16 v[36:39], v[180:183], v[214:217], v[36:39]
	v_mfma_f32_16x16x32_bf16 v[32:35], v[188:191], v[214:217], v[32:35]
	v_mfma_f32_16x16x32_bf16 v[20:23], v[180:183], v[222:225], v[20:23]
	v_mfma_f32_16x16x32_bf16 v[16:19], v[188:191], v[222:225], v[16:19]
	v_mfma_f32_16x16x32_bf16 v[4:7], v[180:183], v[230:233], v[4:7]
	v_mfma_f32_16x16x32_bf16 v[0:3], v[188:191], v[230:233], v[0:3]
	s_setprio 0
	s_barrier
	s_add_i32 s54, 0, 0x18000
	v_add_u32_e32 v140, s54, v165
	s_add_i32 s55, 0, 0x1c000
	ds_read_b128 v[128:131], v140
	ds_read_b128 v[150:153], v140 offset:1024
	ds_read_b128 v[154:157], v140 offset:2048
	ds_read_b128 v[158:161], v140 offset:3072
	v_add_u32_e32 v140, s55, v165
	ds_read_b128 v[176:179], v140
	ds_read_b128 v[180:183], v140 offset:1024
	ds_read_b128 v[184:187], v140 offset:2048
	ds_read_b128 v[188:191], v140 offset:3072
	s_add_u32 s38, s38, 0x40000
	s_addc_u32 s39, s39, 0
	s_mov_b32 m0, s42
	v_lshl_add_u64 v[236:237], s[38:39], 0, v[132:133]
	ds_read_b128 v[202:205], v173 offset:32768
	ds_read_b128 v[206:209], v173 offset:33792
	ds_read_b128 v[210:213], v173 offset:34816
	ds_read_b128 v[214:217], v173 offset:35840
	ds_read_b128 v[218:221], v173 offset:36864
	ds_read_b128 v[222:225], v173 offset:37888
	ds_read_b128 v[226:229], v173 offset:38912
	ds_read_b128 v[230:233], v173 offset:39936
	global_load_lds_dwordx4 v[236:237], off
	v_lshl_add_u64 v[236:237], s[38:39], 0, v[136:137]
	s_mov_b32 m0, s43
	s_nop 0
	global_load_lds_dwordx4 v[236:237], off
	s_waitcnt vmcnt(8)
	s_waitcnt lgkmcnt(0)
	s_barrier
	s_setprio 1
	s_waitcnt lgkmcnt(0)
	v_mfma_f32_16x16x32_bf16 v[124:127], v[128:131], v[202:205], v[124:127]
	v_mfma_f32_16x16x32_bf16 v[120:123], v[154:157], v[202:205], v[120:123]
	v_mfma_f32_16x16x32_bf16 v[108:111], v[128:131], v[210:213], v[108:111]
	v_mfma_f32_16x16x32_bf16 v[104:107], v[154:157], v[210:213], v[104:107]
	v_mfma_f32_16x16x32_bf16 v[92:95], v[128:131], v[218:221], v[92:95]
	v_mfma_f32_16x16x32_bf16 v[88:91], v[154:157], v[218:221], v[88:91]
	v_mfma_f32_16x16x32_bf16 v[76:79], v[128:131], v[226:229], v[76:79]
	v_mfma_f32_16x16x32_bf16 v[72:75], v[154:157], v[226:229], v[72:75]
	v_mfma_f32_16x16x32_bf16 v[124:127], v[150:153], v[206:209], v[124:127]
	v_mfma_f32_16x16x32_bf16 v[120:123], v[158:161], v[206:209], v[120:123]
	v_mfma_f32_16x16x32_bf16 v[108:111], v[150:153], v[214:217], v[108:111]
	v_mfma_f32_16x16x32_bf16 v[104:107], v[158:161], v[214:217], v[104:107]
	v_mfma_f32_16x16x32_bf16 v[92:95], v[150:153], v[222:225], v[92:95]
	v_mfma_f32_16x16x32_bf16 v[88:91], v[158:161], v[222:225], v[88:91]
	v_mfma_f32_16x16x32_bf16 v[76:79], v[150:153], v[230:233], v[76:79]
	v_mfma_f32_16x16x32_bf16 v[72:75], v[158:161], v[230:233], v[72:75]
	s_setprio 0
	s_setprio 1
	v_mfma_f32_16x16x32_bf16 v[116:119], v[176:179], v[202:205], v[116:119]
	v_mfma_f32_16x16x32_bf16 v[112:115], v[184:187], v[202:205], v[112:115]
	v_mfma_f32_16x16x32_bf16 v[100:103], v[176:179], v[210:213], v[100:103]
	v_mfma_f32_16x16x32_bf16 v[96:99], v[184:187], v[210:213], v[96:99]
	v_mfma_f32_16x16x32_bf16 v[84:87], v[176:179], v[218:221], v[84:87]
	v_mfma_f32_16x16x32_bf16 v[80:83], v[184:187], v[218:221], v[80:83]
	v_mfma_f32_16x16x32_bf16 v[68:71], v[176:179], v[226:229], v[68:71]
	v_mfma_f32_16x16x32_bf16 v[64:67], v[184:187], v[226:229], v[64:67]
	v_mfma_f32_16x16x32_bf16 v[116:119], v[180:183], v[206:209], v[116:119]
	v_mfma_f32_16x16x32_bf16 v[112:115], v[188:191], v[206:209], v[112:115]
	v_mfma_f32_16x16x32_bf16 v[100:103], v[180:183], v[214:217], v[100:103]
	v_mfma_f32_16x16x32_bf16 v[96:99], v[188:191], v[214:217], v[96:99]
	v_mfma_f32_16x16x32_bf16 v[84:87], v[180:183], v[222:225], v[84:87]
	v_mfma_f32_16x16x32_bf16 v[80:83], v[188:191], v[222:225], v[80:83]
	v_mfma_f32_16x16x32_bf16 v[68:71], v[180:183], v[230:233], v[68:71]
	v_mfma_f32_16x16x32_bf16 v[64:67], v[188:191], v[230:233], v[64:67]
	s_setprio 0
	s_barrier
; #define PG8_STAGE(bufoff, gbase, voff) do { _Pragma("unroll") for (int _i = 0; _i < 2; ++_i) \
;         __builtin_amdgcn_global_load_lds((const unsigned*)((const char*)(gbase) + (voff)[_i]), (PG8_LAS unsigned*)(lds + (bufoff) + ldsw + _i * 8192), 16, 0, 0); } while (0)
; #define PG8_LDA(dst, b, h) do { _Pragma("unroll") for (int m = 0; m < 4; ++m) _Pragma("unroll") for (int k = 0; k < 2; ++k) dst[m][k] = *(const PG8_LAS bf16x8*)(lds + PG8_SA(b, h) + aoff + m * 2048 + k * 1024); } while (0)
; #define PG8_MMA(ai, bj, At, Bt) do { __builtin_amdgcn_s_setprio(1); _Pragma("unroll") for (int m = 0; m < 4; ++m) _Pragma("unroll") for (int n = 0; n < 2; ++n) _Pragma("unroll") for (int k = 0; k < 2; ++k) \
;         acc[ai][bj][m][n] = __builtin_amdgcn_mfma_f32_16x16x32_bf16(Bt[n][k], At[m][k], acc[ai][bj][m][n], 0, 0, 0); __builtin_amdgcn_s_setprio(0); } while (0)
; #define PG8_WAIT_V(n) asm volatile("s_waitcnt vmcnt(" #n ")" ::: "memory")
; #define PG8_WAIT_L(n) asm volatile("s_waitcnt lgkmcnt(" #n ")" ::: "memory")
; #define PG8_BAR __builtin_amdgcn_s_barrier()
; #define PG8_SCHED __builtin_amdgcn_sched_barrier(0)
; template <class Epi, class Sched, bool ALIGN_EPI = false, bool SP2 = false>
; __device__ __forceinline__ void gemm_phase(PG8_LAS unsigned char* lds, const Gemm g, const Sched& S, const Epi& E) {
;     ...
;             PG8_LDA(At, 1, 1); PG8_STAGE(PG8_SB(1, 0), b3, voffB); PG8_STAGE(PG8_SB(1, 1), b3 + hstep, voffB); PG8_STAGE(PG8_SA(1, 0), a3, voffA);
;             PG8_WAIT_V(8); PG8_WAIT_L(0); PG8_BAR; PG8_MMA(1, 0, At, B0); PG8_MMA(1, 1, At, B1); PG8_BAR; PG8_SCHED;
	s_add_i32 s38, s54, s40
	v_lshl_add_u64 v[162:163], v[162:163], 0, s[10:11]
	s_mov_b32 m0, s38
	ds_read_b128 v[202:205], v173 offset:49152
	ds_read_b128 v[206:209], v173 offset:50176
	ds_read_b128 v[210:213], v173 offset:51200
	ds_read_b128 v[214:217], v173 offset:52224
	ds_read_b128 v[218:221], v173 offset:53248
	ds_read_b128 v[222:225], v173 offset:54272
	ds_read_b128 v[226:229], v173 offset:55296
	ds_read_b128 v[230:233], v173 offset:56320
	global_load_lds_dwordx4 v[162:163], off
	s_add_i32 m0, s38, 0x2000
	s_add_u32 s36, s36, 0x40080
	v_lshl_add_u64 v[162:163], v[192:193], 0, s[10:11]
	s_addc_u32 s37, s37, 0
	s_add_i32 s38, s55, s40
	global_load_lds_dwordx4 v[162:163], off
	v_lshl_add_u64 v[162:163], s[36:37], 0, v[134:135]
	s_mov_b32 m0, s38
	s_nop 0
	global_load_lds_dwordx4 v[162:163], off
	v_lshl_add_u64 v[162:163], s[36:37], 0, v[138:139]
	s_add_i32 m0, s38, 0x2000
	s_nop 0
	global_load_lds_dwordx4 v[162:163], off
	v_lshl_add_u64 v[162:163], v[196:197], 0, s[10:11]
	s_mov_b32 m0, s45
	s_nop 0
	global_load_lds_dwordx4 v[162:163], off
	v_lshl_add_u64 v[162:163], v[234:235], 0, s[10:11]
	s_mov_b32 m0, s46
	s_nop 0
	global_load_lds_dwordx4 v[162:163], off
	s_waitcnt vmcnt(8)
	s_waitcnt lgkmcnt(0)
	s_barrier
	s_setprio 1
	s_waitcnt lgkmcnt(0)
	v_mfma_f32_16x16x32_bf16 v[60:63], v[128:131], v[202:205], v[60:63]
	v_mfma_f32_16x16x32_bf16 v[56:59], v[154:157], v[202:205], v[56:59]
	v_mfma_f32_16x16x32_bf16 v[44:47], v[128:131], v[210:213], v[44:47]
	v_mfma_f32_16x16x32_bf16 v[40:43], v[154:157], v[210:213], v[40:43]
	v_mfma_f32_16x16x32_bf16 v[28:31], v[128:131], v[218:221], v[28:31]
	v_mfma_f32_16x16x32_bf16 v[24:27], v[154:157], v[218:221], v[24:27]
	v_mfma_f32_16x16x32_bf16 v[12:15], v[128:131], v[226:229], v[12:15]
	v_mfma_f32_16x16x32_bf16 v[8:11], v[154:157], v[226:229], v[8:11]
	v_mfma_f32_16x16x32_bf16 v[60:63], v[150:153], v[206:209], v[60:63]
	v_mfma_f32_16x16x32_bf16 v[56:59], v[158:161], v[206:209], v[56:59]
	v_mfma_f32_16x16x32_bf16 v[44:47], v[150:153], v[214:217], v[44:47]
	v_mfma_f32_16x16x32_bf16 v[40:43], v[158:161], v[214:217], v[40:43]
	v_mfma_f32_16x16x32_bf16 v[28:31], v[150:153], v[222:225], v[28:31]
	v_mfma_f32_16x16x32_bf16 v[24:27], v[158:161], v[222:225], v[24:27]
	v_mfma_f32_16x16x32_bf16 v[12:15], v[150:153], v[230:233], v[12:15]
	v_mfma_f32_16x16x32_bf16 v[8:11], v[158:161], v[230:233], v[8:11]
	s_setprio 0
	s_setprio 1
	v_mfma_f32_16x16x32_bf16 v[52:55], v[176:179], v[202:205], v[52:55]
	s_add_i32 s53, s53, 2
	s_add_u32 s0, s0, 0x100
	s_addc_u32 s1, s1, 0
	s_add_u32 s51, s51, 0x100
	s_addc_u32 s52, s52, 0
	v_mfma_f32_16x16x32_bf16 v[48:51], v[184:187], v[202:205], v[48:51]
	v_mfma_f32_16x16x32_bf16 v[36:39], v[176:179], v[210:213], v[36:39]
	v_mfma_f32_16x16x32_bf16 v[32:35], v[184:187], v[210:213], v[32:35]
	v_mfma_f32_16x16x32_bf16 v[20:23], v[176:179], v[218:221], v[20:23]
	v_mfma_f32_16x16x32_bf16 v[16:19], v[184:187], v[218:221], v[16:19]
	v_mfma_f32_16x16x32_bf16 v[4:7], v[176:179], v[226:229], v[4:7]
	v_mfma_f32_16x16x32_bf16 v[0:3], v[184:187], v[226:229], v[0:3]
	v_mfma_f32_16x16x32_bf16 v[52:55], v[180:183], v[206:209], v[52:55]
	v_mfma_f32_16x16x32_bf16 v[48:51], v[188:191], v[206:209], v[48:51]
	v_mfma_f32_16x16x32_bf16 v[36:39], v[180:183], v[214:217], v[36:39]
	v_mfma_f32_16x16x32_bf16 v[32:35], v[188:191], v[214:217], v[32:35]
	v_mfma_f32_16x16x32_bf16 v[20:23], v[180:183], v[222:225], v[20:23]
	v_mfma_f32_16x16x32_bf16 v[16:19], v[188:191], v[222:225], v[16:19]
	v_mfma_f32_16x16x32_bf16 v[4:7], v[180:183], v[230:233], v[4:7]
	v_mfma_f32_16x16x32_bf16 v[0:3], v[188:191], v[230:233], v[0:3]
	s_setprio 0
	s_barrier
	s_cmp_gt_u32 s53, 13
	s_cbranch_scc0 .LBB0_369
	s_and_b64 vcc, exec, s[12:13]
	s_cbranch_vccz .LBB0_372
	s_barrier

; #define PG8_STAGE(bufoff, gbase, voff) do { _Pragma("unroll") for (int _i = 0; _i < 2; ++_i) \
;         __builtin_amdgcn_global_load_lds((const unsigned*)((const char*)(gbase) + (voff)[_i]), (PG8_LAS unsigned*)(lds + (bufoff) + ldsw + _i * 8192), 16, 0, 0); } while (0)
; #define PG8_LDA(dst, b, h) do { _Pragma("unroll") for (int m = 0; m < 4; ++m) _Pragma("unroll") for (int k = 0; k < 2; ++k) dst[m][k] = *(const PG8_LAS bf16x8*)(lds + PG8_SA(b, h) + aoff + m * 2048 + k * 1024); } while (0)
; #define PG8_LDB(dst, b, h) do { _Pragma("unroll") for (int n = 0; n < 2; ++n) _Pragma("unroll") for (int k = 0; k < 2; ++k) dst[n][k] = *(const PG8_LAS bf16x8*)(lds + PG8_SB(b, h) + boff + n * 2048 + k * 1024); } while (0)
; #define PG8_MMA(ai, bj, At, Bt) do { __builtin_amdgcn_s_setprio(1); _Pragma("unroll") for (int m = 0; m < 4; ++m) _Pragma("unroll") for (int n = 0; n < 2; ++n) _Pragma("unroll") for (int k = 0; k < 2; ++k) \
;         acc[ai][bj][m][n] = __builtin_amdgcn_mfma_f32_16x16x32_bf16(Bt[n][k], At[m][k], acc[ai][bj][m][n], 0, 0, 0); __builtin_amdgcn_s_setprio(0); } while (0)
; #define PG8_WAIT_V(n) asm volatile("s_waitcnt vmcnt(" #n ")" ::: "memory")
; #define PG8_WAIT_L(n) asm volatile("s_waitcnt lgkmcnt(" #n ")" ::: "memory")
; #define PG8_BAR __builtin_amdgcn_s_barrier()
; #define PG8_SCHED __builtin_amdgcn_sched_barrier(0)
; template <class Epi, class Sched, bool ALIGN_EPI = false, bool SP2 = false>
; __device__ __forceinline__ void gemm_phase(PG8_LAS unsigned char* lds, const Gemm g, const Sched& S, const Epi& E) {
;     ...
;             PG8_LDB(B0, 0, 0); PG8_LDB(B1, 0, 1); PG8_SCHED; PG8_LDA(At, 0, 0); PG8_STAGE(PG8_SA(1, 1), a1 + hstep, voffA);
;             PG8_WAIT_V(8); PG8_WAIT_L(0); PG8_BAR; PG8_MMA(0, 0, At, B0); PG8_MMA(0, 1, At, B1); PG8_BAR; PG8_SCHED;
;             PG8_LDA(At, 0, 1); PG8_STAGE(PG8_SB(0, 0), b2, voffB); PG8_STAGE(PG8_SB(0, 1), b2 + hstep, voffB); PG8_STAGE(PG8_SA(0, 0), a2, voffA);
;             PG8_WAIT_V(8); PG8_WAIT_L(0); PG8_BAR; PG8_MMA(1, 0, At, B0); PG8_MMA(1, 1, At, B1); PG8_BAR; PG8_SCHED;
.LBB0_699:
	ds_read_b128 v[128:131], v222
	ds_read_b128 v[132:135], v222 offset:1024
	ds_read_b128 v[136:139], v222 offset:2048
	ds_read_b128 v[140:143], v222 offset:3072
	ds_read_b128 v[144:147], v223
	ds_read_b128 v[148:151], v223 offset:1024
	ds_read_b128 v[152:155], v223 offset:2048
	ds_read_b128 v[156:159], v223 offset:3072
	s_add_u32 s34, s0, 0xfffc0080
	s_addc_u32 s35, s1, -1
	s_cmp_eq_u32 s65, 12
	s_cselect_b32 s37, s25, s35
	s_cselect_b32 s36, s31, s34
	s_cselect_b32 s35, s23, s63
	s_cselect_b32 s34, s33, s62
	v_lshl_add_u64 v[244:245], s[0:1], 0, v[182:183]
	s_add_i32 m0, s39, 0xc000
	ds_read_b128 v[160:163], v224
	ds_read_b128 v[164:167], v224 offset:1024
	ds_read_b128 v[190:193], v224 offset:2048
	ds_read_b128 v[194:197], v224 offset:3072
	ds_read_b128 v[228:231], v224 offset:4096
	ds_read_b128 v[232:235], v224 offset:5120
	ds_read_b128 v[236:239], v224 offset:6144
	ds_read_b128 v[240:243], v224 offset:7168
	global_load_lds_dwordx4 v[244:245], off
	v_lshl_add_u64 v[244:245], s[0:1], 0, v[184:185]
	s_add_i32 m0, s39, 0xe000
	s_nop 0
	global_load_lds_dwordx4 v[244:245], off
	s_waitcnt vmcnt(8)
	s_waitcnt lgkmcnt(0)
	s_barrier
	s_setprio 1
	s_waitcnt lgkmcnt(0)
	v_mfma_f32_16x16x32_bf16 v[124:127], v[128:131], v[160:163], v[124:127]
	v_mfma_f32_16x16x32_bf16 v[120:123], v[136:139], v[160:163], v[120:123]
	v_mfma_f32_16x16x32_bf16 v[108:111], v[128:131], v[190:193], v[108:111]
	v_mfma_f32_16x16x32_bf16 v[104:107], v[136:139], v[190:193], v[104:107]
	v_mfma_f32_16x16x32_bf16 v[92:95], v[128:131], v[228:231], v[92:95]
	v_mfma_f32_16x16x32_bf16 v[88:91], v[136:139], v[228:231], v[88:91]
	v_mfma_f32_16x16x32_bf16 v[76:79], v[128:131], v[236:239], v[76:79]
	v_mfma_f32_16x16x32_bf16 v[72:75], v[136:139], v[236:239], v[72:75]
	v_mfma_f32_16x16x32_bf16 v[124:127], v[132:135], v[164:167], v[124:127]
	v_mfma_f32_16x16x32_bf16 v[120:123], v[140:143], v[164:167], v[120:123]
	v_mfma_f32_16x16x32_bf16 v[108:111], v[132:135], v[194:197], v[108:111]
	v_mfma_f32_16x16x32_bf16 v[104:107], v[140:143], v[194:197], v[104:107]
	v_mfma_f32_16x16x32_bf16 v[92:95], v[132:135], v[232:235], v[92:95]
	v_mfma_f32_16x16x32_bf16 v[88:91], v[140:143], v[232:235], v[88:91]
	v_mfma_f32_16x16x32_bf16 v[76:79], v[132:135], v[240:243], v[76:79]
	v_mfma_f32_16x16x32_bf16 v[72:75], v[140:143], v[240:243], v[72:75]
	s_setprio 0
	s_setprio 1
	v_mfma_f32_16x16x32_bf16 v[116:119], v[144:147], v[160:163], v[116:119]
	v_mfma_f32_16x16x32_bf16 v[112:115], v[152:155], v[160:163], v[112:115]
	v_mfma_f32_16x16x32_bf16 v[100:103], v[144:147], v[190:193], v[100:103]
	v_mfma_f32_16x16x32_bf16 v[96:99], v[152:155], v[190:193], v[96:99]
	v_mfma_f32_16x16x32_bf16 v[84:87], v[144:147], v[228:231], v[84:87]
	v_mfma_f32_16x16x32_bf16 v[80:83], v[152:155], v[228:231], v[80:83]
	v_mfma_f32_16x16x32_bf16 v[68:71], v[144:147], v[236:239], v[68:71]
	v_mfma_f32_16x16x32_bf16 v[64:67], v[152:155], v[236:239], v[64:67]
	v_mfma_f32_16x16x32_bf16 v[116:119], v[148:151], v[164:167], v[116:119]
	v_mfma_f32_16x16x32_bf16 v[112:115], v[156:159], v[164:167], v[112:115]
	v_mfma_f32_16x16x32_bf16 v[100:103], v[148:151], v[194:197], v[100:103]
	v_mfma_f32_16x16x32_bf16 v[96:99], v[156:159], v[194:197], v[96:99]
	v_mfma_f32_16x16x32_bf16 v[84:87], v[148:151], v[232:235], v[84:87]
	v_mfma_f32_16x16x32_bf16 v[80:83], v[156:159], v[232:235], v[80:83]
	v_mfma_f32_16x16x32_bf16 v[68:71], v[148:151], v[240:243], v[68:71]
	v_mfma_f32_16x16x32_bf16 v[64:67], v[156:159], v[240:243], v[64:67]
	s_setprio 0
	s_barrier
	s_add_i32 s66, s46, s38
	v_lshl_add_u64 v[244:245], s[34:35], 0, v[174:175]
	s_mov_b32 m0, s66
	ds_read_b128 v[160:163], v224 offset:16384
	ds_read_b128 v[164:167], v224 offset:17408
	ds_read_b128 v[190:193], v224 offset:18432
	ds_read_b128 v[194:197], v224 offset:19456
	ds_read_b128 v[228:231], v224 offset:20480
	ds_read_b128 v[232:235], v224 offset:21504
	ds_read_b128 v[236:239], v224 offset:22528
	ds_read_b128 v[240:243], v224 offset:23552
	global_load_lds_dwordx4 v[244:245], off
	s_add_i32 m0, s66, 0x2000
	s_add_u32 s66, s34, 0x40000
	v_lshl_add_u64 v[246:247], s[34:35], 0, v[178:179]
	s_addc_u32 s67, s35, 0
	s_add_i32 s68, s56, s38
	global_load_lds_dwordx4 v[246:247], off
	v_lshl_add_u64 v[248:249], s[66:67], 0, v[174:175]
	s_mov_b32 m0, s68
	v_lshl_add_u64 v[250:251], s[36:37], 0, v[176:177]
	global_load_lds_dwordx4 v[248:249], off
	v_lshl_add_u64 v[248:249], s[66:67], 0, v[178:179]
	s_add_i32 m0, s68, 0x2000
	s_nop 0
	global_load_lds_dwordx4 v[248:249], off
	v_lshl_add_u64 v[248:249], s[36:37], 0, v[172:173]
	s_mov_b32 m0, s39
	s_nop 0
	global_load_lds_dwordx4 v[248:249], off
	s_mov_b32 m0, s40
	s_nop 0
	global_load_lds_dwordx4 v[250:251], off
	s_waitcnt vmcnt(8)
	s_waitcnt lgkmcnt(0)
	s_barrier
; #define PG8_STAGE(bufoff, gbase, voff) do { _Pragma("unroll") for (int _i = 0; _i < 2; ++_i) \
;         __builtin_amdgcn_global_load_lds((const unsigned*)((const char*)(gbase) + (voff)[_i]), (PG8_LAS unsigned*)(lds + (bufoff) + ldsw + _i * 8192), 16, 0, 0); } while (0)
; #define PG8_LDA(dst, b, h) do { _Pragma("unroll") for (int m = 0; m < 4; ++m) _Pragma("unroll") for (int k = 0; k < 2; ++k) dst[m][k] = *(const PG8_LAS bf16x8*)(lds + PG8_SA(b, h) + aoff + m * 2048 + k * 1024); } while (0)
; #define PG8_LDB(dst, b, h) do { _Pragma("unroll") for (int n = 0; n < 2; ++n) _Pragma("unroll") for (int k = 0; k < 2; ++k) dst[n][k] = *(const PG8_LAS bf16x8*)(lds + PG8_SB(b, h) + boff + n * 2048 + k * 1024); } while (0)
; #define PG8_MMA(ai, bj, At, Bt) do { __builtin_amdgcn_s_setprio(1); _Pragma("unroll") for (int m = 0; m < 4; ++m) _Pragma("unroll") for (int n = 0; n < 2; ++n) _Pragma("unroll") for (int k = 0; k < 2; ++k) \
;         acc[ai][bj][m][n] = __builtin_amdgcn_mfma_f32_16x16x32_bf16(Bt[n][k], At[m][k], acc[ai][bj][m][n], 0, 0, 0); __builtin_amdgcn_s_setprio(0); } while (0)
; #define PG8_WAIT_V(n) asm volatile("s_waitcnt vmcnt(" #n ")" ::: "memory")
; #define PG8_WAIT_L(n) asm volatile("s_waitcnt lgkmcnt(" #n ")" ::: "memory")
; #define PG8_BAR __builtin_amdgcn_s_barrier()
; #define PG8_SCHED __builtin_amdgcn_sched_barrier(0)
; template <class Epi, class Sched, bool ALIGN_EPI = false, bool SP2 = false>
; __device__ __forceinline__ void gemm_phase(PG8_LAS unsigned char* lds, const Gemm g, const Sched& S, const Epi& E) {
;     ...
;             PG8_WAIT_V(8); PG8_WAIT_L(0); PG8_BAR; PG8_MMA(1, 0, At, B0); PG8_MMA(1, 1, At, B1); PG8_BAR; PG8_SCHED;
;             PG8_LDB(B0, 1, 0); PG8_LDB(B1, 1, 1); PG8_SCHED; PG8_LDA(At, 1, 0); PG8_STAGE(PG8_SA(0, 1), a2 + hstep, voffA);
;             PG8_WAIT_V(8); PG8_WAIT_L(0); PG8_BAR; PG8_MMA(0, 0, At, B0); PG8_MMA(0, 1, At, B1); PG8_BAR; PG8_SCHED;
	s_setprio 1
	s_waitcnt lgkmcnt(0)
	v_mfma_f32_16x16x32_bf16 v[60:63], v[128:131], v[160:163], v[60:63]
	v_mfma_f32_16x16x32_bf16 v[56:59], v[136:139], v[160:163], v[56:59]
	v_mfma_f32_16x16x32_bf16 v[44:47], v[128:131], v[190:193], v[44:47]
	v_mfma_f32_16x16x32_bf16 v[40:43], v[136:139], v[190:193], v[40:43]
	v_mfma_f32_16x16x32_bf16 v[28:31], v[128:131], v[228:231], v[28:31]
	v_mfma_f32_16x16x32_bf16 v[24:27], v[136:139], v[228:231], v[24:27]
	v_mfma_f32_16x16x32_bf16 v[12:15], v[128:131], v[236:239], v[12:15]
	v_mfma_f32_16x16x32_bf16 v[8:11], v[136:139], v[236:239], v[8:11]
	v_mfma_f32_16x16x32_bf16 v[60:63], v[132:135], v[164:167], v[60:63]
	v_mfma_f32_16x16x32_bf16 v[56:59], v[140:143], v[164:167], v[56:59]
	v_mfma_f32_16x16x32_bf16 v[44:47], v[132:135], v[194:197], v[44:47]
	v_mfma_f32_16x16x32_bf16 v[40:43], v[140:143], v[194:197], v[40:43]
	v_mfma_f32_16x16x32_bf16 v[28:31], v[132:135], v[232:235], v[28:31]
	v_mfma_f32_16x16x32_bf16 v[24:27], v[140:143], v[232:235], v[24:27]
	v_mfma_f32_16x16x32_bf16 v[12:15], v[132:135], v[240:243], v[12:15]
	v_mfma_f32_16x16x32_bf16 v[8:11], v[140:143], v[240:243], v[8:11]
	s_setprio 0
	s_setprio 1
	v_mfma_f32_16x16x32_bf16 v[52:55], v[144:147], v[160:163], v[52:55]
	v_mfma_f32_16x16x32_bf16 v[48:51], v[152:155], v[160:163], v[48:51]
	v_mfma_f32_16x16x32_bf16 v[36:39], v[144:147], v[190:193], v[36:39]
	v_mfma_f32_16x16x32_bf16 v[32:35], v[152:155], v[190:193], v[32:35]
	v_mfma_f32_16x16x32_bf16 v[20:23], v[144:147], v[228:231], v[20:23]
	v_mfma_f32_16x16x32_bf16 v[16:19], v[152:155], v[228:231], v[16:19]
	v_mfma_f32_16x16x32_bf16 v[4:7], v[144:147], v[236:239], v[4:7]
	v_mfma_f32_16x16x32_bf16 v[0:3], v[152:155], v[236:239], v[0:3]
	v_mfma_f32_16x16x32_bf16 v[52:55], v[148:151], v[164:167], v[52:55]
	v_mfma_f32_16x16x32_bf16 v[48:51], v[156:159], v[164:167], v[48:51]
	v_mfma_f32_16x16x32_bf16 v[36:39], v[148:151], v[194:197], v[36:39]
	v_mfma_f32_16x16x32_bf16 v[32:35], v[156:159], v[194:197], v[32:35]
	v_mfma_f32_16x16x32_bf16 v[20:23], v[148:151], v[232:235], v[20:23]
	v_mfma_f32_16x16x32_bf16 v[16:19], v[156:159], v[232:235], v[16:19]
	v_mfma_f32_16x16x32_bf16 v[4:7], v[148:151], v[240:243], v[4:7]
	v_mfma_f32_16x16x32_bf16 v[0:3], v[156:159], v[240:243], v[0:3]
	s_setprio 0
	s_barrier
	s_add_i32 s66, 0, 0x18000
	s_add_i32 s67, 0, 0x1c000
	v_add_u32_e32 v140, s66, v204
	v_add_u32_e32 v156, s67, v204
	ds_read_b128 v[128:131], v140
	ds_read_b128 v[132:135], v140 offset:1024
	ds_read_b128 v[136:139], v140 offset:2048
	ds_read_b128 v[140:143], v140 offset:3072
	ds_read_b128 v[144:147], v156
	ds_read_b128 v[148:151], v156 offset:1024
	ds_read_b128 v[152:155], v156 offset:2048
	ds_read_b128 v[156:159], v156 offset:3072
	s_add_u32 s36, s36, 0x40000
	s_addc_u32 s37, s37, 0
	s_mov_b32 m0, s41
	v_lshl_add_u64 v[252:253], s[36:37], 0, v[172:173]
	ds_read_b128 v[160:163], v224 offset:32768
	ds_read_b128 v[164:167], v224 offset:33792
	ds_read_b128 v[190:193], v224 offset:34816
	ds_read_b128 v[194:197], v224 offset:35840
	ds_read_b128 v[228:231], v224 offset:36864
	ds_read_b128 v[232:235], v224 offset:37888
	ds_read_b128 v[236:239], v224 offset:38912
	ds_read_b128 v[240:243], v224 offset:39936
	global_load_lds_dwordx4 v[252:253], off
	v_lshl_add_u64 v[252:253], s[36:37], 0, v[176:177]
	s_mov_b32 m0, s42
	s_nop 0
	global_load_lds_dwordx4 v[252:253], off
	s_waitcnt vmcnt(8)
	s_waitcnt lgkmcnt(0)
	s_barrier
	s_setprio 1
	s_waitcnt lgkmcnt(0)
	v_mfma_f32_16x16x32_bf16 v[124:127], v[128:131], v[160:163], v[124:127]
	v_mfma_f32_16x16x32_bf16 v[120:123], v[136:139], v[160:163], v[120:123]
	v_mfma_f32_16x16x32_bf16 v[108:111], v[128:131], v[190:193], v[108:111]
	v_mfma_f32_16x16x32_bf16 v[104:107], v[136:139], v[190:193], v[104:107]
	v_mfma_f32_16x16x32_bf16 v[92:95], v[128:131], v[228:231], v[92:95]
	v_mfma_f32_16x16x32_bf16 v[88:91], v[136:139], v[228:231], v[88:91]
	v_mfma_f32_16x16x32_bf16 v[76:79], v[128:131], v[236:239], v[76:79]
	v_mfma_f32_16x16x32_bf16 v[72:75], v[136:139], v[236:239], v[72:75]
	v_mfma_f32_16x16x32_bf16 v[124:127], v[132:135], v[164:167], v[124:127]
	v_mfma_f32_16x16x32_bf16 v[120:123], v[140:143], v[164:167], v[120:123]
	v_mfma_f32_16x16x32_bf16 v[108:111], v[132:135], v[194:197], v[108:111]
	v_mfma_f32_16x16x32_bf16 v[104:107], v[140:143], v[194:197], v[104:107]
	v_mfma_f32_16x16x32_bf16 v[92:95], v[132:135], v[232:235], v[92:95]
	v_mfma_f32_16x16x32_bf16 v[88:91], v[140:143], v[232:235], v[88:91]
	v_mfma_f32_16x16x32_bf16 v[76:79], v[132:135], v[240:243], v[76:79]
	v_mfma_f32_16x16x32_bf16 v[72:75], v[140:143], v[240:243], v[72:75]
	s_setprio 0
	s_setprio 1
	v_mfma_f32_16x16x32_bf16 v[116:119], v[144:147], v[160:163], v[116:119]
	v_mfma_f32_16x16x32_bf16 v[112:115], v[152:155], v[160:163], v[112:115]
	v_mfma_f32_16x16x32_bf16 v[100:103], v[144:147], v[190:193], v[100:103]
	v_mfma_f32_16x16x32_bf16 v[96:99], v[152:155], v[190:193], v[96:99]
	v_mfma_f32_16x16x32_bf16 v[84:87], v[144:147], v[228:231], v[84:87]
	v_mfma_f32_16x16x32_bf16 v[80:83], v[152:155], v[228:231], v[80:83]
	v_mfma_f32_16x16x32_bf16 v[68:71], v[144:147], v[236:239], v[68:71]
	v_mfma_f32_16x16x32_bf16 v[64:67], v[152:155], v[236:239], v[64:67]
	v_mfma_f32_16x16x32_bf16 v[116:119], v[148:151], v[164:167], v[116:119]
	v_mfma_f32_16x16x32_bf16 v[112:115], v[156:159], v[164:167], v[112:115]
	v_mfma_f32_16x16x32_bf16 v[100:103], v[148:151], v[194:197], v[100:103]
	v_mfma_f32_16x16x32_bf16 v[96:99], v[156:159], v[194:197], v[96:99]
	v_mfma_f32_16x16x32_bf16 v[84:87], v[148:151], v[232:235], v[84:87]
	v_mfma_f32_16x16x32_bf16 v[80:83], v[156:159], v[232:235], v[80:83]
	v_mfma_f32_16x16x32_bf16 v[68:71], v[148:151], v[240:243], v[68:71]
	v_mfma_f32_16x16x32_bf16 v[64:67], v[156:159], v[240:243], v[64:67]
	s_setprio 0
	s_barrier
; #define PG8_STAGE(bufoff, gbase, voff) do { _Pragma("unroll") for (int _i = 0; _i < 2; ++_i) \
;         __builtin_amdgcn_global_load_lds((const unsigned*)((const char*)(gbase) + (voff)[_i]), (PG8_LAS unsigned*)(lds + (bufoff) + ldsw + _i * 8192), 16, 0, 0); } while (0)
; #define PG8_LDA(dst, b, h) do { _Pragma("unroll") for (int m = 0; m < 4; ++m) _Pragma("unroll") for (int k = 0; k < 2; ++k) dst[m][k] = *(const PG8_LAS bf16x8*)(lds + PG8_SA(b, h) + aoff + m * 2048 + k * 1024); } while (0)
; #define PG8_MMA(ai, bj, At, Bt) do { __builtin_amdgcn_s_setprio(1); _Pragma("unroll") for (int m = 0; m < 4; ++m) _Pragma("unroll") for (int n = 0; n < 2; ++n) _Pragma("unroll") for (int k = 0; k < 2; ++k) \
;         acc[ai][bj][m][n] = __builtin_amdgcn_mfma_f32_16x16x32_bf16(Bt[n][k], At[m][k], acc[ai][bj][m][n], 0, 0, 0); __builtin_amdgcn_s_setprio(0); } while (0)
; #define PG8_WAIT_V(n) asm volatile("s_waitcnt vmcnt(" #n ")" ::: "memory")
; #define PG8_WAIT_L(n) asm volatile("s_waitcnt lgkmcnt(" #n ")" ::: "memory")
; #define PG8_BAR __builtin_amdgcn_s_barrier()
; #define PG8_SCHED __builtin_amdgcn_sched_barrier(0)
; template <class Epi, class Sched, bool ALIGN_EPI = false, bool SP2 = false>
; __device__ __forceinline__ void gemm_phase(PG8_LAS unsigned char* lds, const Gemm g, const Sched& S, const Epi& E) {
;     ...
;             PG8_LDA(At, 1, 1); PG8_STAGE(PG8_SB(1, 0), b3, voffB); PG8_STAGE(PG8_SB(1, 1), b3 + hstep, voffB); PG8_STAGE(PG8_SA(1, 0), a3, voffA);
;             PG8_WAIT_V(8); PG8_WAIT_L(0); PG8_BAR; PG8_MMA(1, 0, At, B0); PG8_MMA(1, 1, At, B1); PG8_BAR; PG8_SCHED;
	s_add_i32 s36, s66, s38
	v_lshl_add_u64 v[244:245], v[244:245], 0, s[16:17]
	s_mov_b32 m0, s36
	ds_read_b128 v[160:163], v224 offset:49152
	ds_read_b128 v[164:167], v224 offset:50176
	ds_read_b128 v[190:193], v224 offset:51200
	ds_read_b128 v[194:197], v224 offset:52224
	ds_read_b128 v[228:231], v224 offset:53248
	ds_read_b128 v[232:235], v224 offset:54272
	ds_read_b128 v[236:239], v224 offset:55296
	ds_read_b128 v[240:243], v224 offset:56320
	global_load_lds_dwordx4 v[244:245], off
	s_add_i32 m0, s36, 0x2000
	s_add_u32 s34, s34, 0x40080
	v_lshl_add_u64 v[244:245], v[246:247], 0, s[16:17]
	s_addc_u32 s35, s35, 0
	s_add_i32 s36, s67, s38
	global_load_lds_dwordx4 v[244:245], off
	v_lshl_add_u64 v[244:245], s[34:35], 0, v[174:175]
	s_mov_b32 m0, s36
	s_nop 0
	global_load_lds_dwordx4 v[244:245], off
	v_lshl_add_u64 v[244:245], s[34:35], 0, v[178:179]
	s_add_i32 m0, s36, 0x2000
	s_nop 0
	global_load_lds_dwordx4 v[244:245], off
	v_lshl_add_u64 v[244:245], v[248:249], 0, s[16:17]
	s_mov_b32 m0, s50
	s_nop 0
	global_load_lds_dwordx4 v[244:245], off
	v_lshl_add_u64 v[244:245], v[250:251], 0, s[16:17]
	s_mov_b32 m0, s51
	s_nop 0
	global_load_lds_dwordx4 v[244:245], off
	s_waitcnt vmcnt(8)
	s_waitcnt lgkmcnt(0)
	s_barrier
	s_setprio 1
	s_waitcnt lgkmcnt(0)
	v_mfma_f32_16x16x32_bf16 v[60:63], v[128:131], v[160:163], v[60:63]
	v_mfma_f32_16x16x32_bf16 v[56:59], v[136:139], v[160:163], v[56:59]
	v_mfma_f32_16x16x32_bf16 v[44:47], v[128:131], v[190:193], v[44:47]
	v_mfma_f32_16x16x32_bf16 v[40:43], v[136:139], v[190:193], v[40:43]
	v_mfma_f32_16x16x32_bf16 v[28:31], v[128:131], v[228:231], v[28:31]
	v_mfma_f32_16x16x32_bf16 v[24:27], v[136:139], v[228:231], v[24:27]
	v_mfma_f32_16x16x32_bf16 v[12:15], v[128:131], v[236:239], v[12:15]
	v_mfma_f32_16x16x32_bf16 v[8:11], v[136:139], v[236:239], v[8:11]
	v_mfma_f32_16x16x32_bf16 v[60:63], v[132:135], v[164:167], v[60:63]
	v_mfma_f32_16x16x32_bf16 v[56:59], v[140:143], v[164:167], v[56:59]
	v_mfma_f32_16x16x32_bf16 v[44:47], v[132:135], v[194:197], v[44:47]
	v_mfma_f32_16x16x32_bf16 v[40:43], v[140:143], v[194:197], v[40:43]
	v_mfma_f32_16x16x32_bf16 v[28:31], v[132:135], v[232:235], v[28:31]
	v_mfma_f32_16x16x32_bf16 v[24:27], v[140:143], v[232:235], v[24:27]
	v_mfma_f32_16x16x32_bf16 v[12:15], v[132:135], v[240:243], v[12:15]
	v_mfma_f32_16x16x32_bf16 v[8:11], v[140:143], v[240:243], v[8:11]
	s_setprio 0
	s_setprio 1
	v_mfma_f32_16x16x32_bf16 v[52:55], v[144:147], v[160:163], v[52:55]
	s_add_i32 s65, s65, 2
	s_add_u32 s0, s0, 0x100
	s_addc_u32 s1, s1, 0
	s_add_u32 s62, s62, 0x100
	s_addc_u32 s63, s63, 0
	v_mfma_f32_16x16x32_bf16 v[48:51], v[152:155], v[160:163], v[48:51]
	v_mfma_f32_16x16x32_bf16 v[36:39], v[144:147], v[190:193], v[36:39]
	v_mfma_f32_16x16x32_bf16 v[32:35], v[152:155], v[190:193], v[32:35]
	v_mfma_f32_16x16x32_bf16 v[20:23], v[144:147], v[228:231], v[20:23]
	v_mfma_f32_16x16x32_bf16 v[16:19], v[152:155], v[228:231], v[16:19]
	v_mfma_f32_16x16x32_bf16 v[4:7], v[144:147], v[236:239], v[4:7]
	v_mfma_f32_16x16x32_bf16 v[0:3], v[152:155], v[236:239], v[0:3]
	v_mfma_f32_16x16x32_bf16 v[52:55], v[148:151], v[164:167], v[52:55]
	v_mfma_f32_16x16x32_bf16 v[48:51], v[156:159], v[164:167], v[48:51]
	v_mfma_f32_16x16x32_bf16 v[36:39], v[148:151], v[194:197], v[36:39]
	v_mfma_f32_16x16x32_bf16 v[32:35], v[156:159], v[194:197], v[32:35]
	v_mfma_f32_16x16x32_bf16 v[20:23], v[148:151], v[232:235], v[20:23]
	v_mfma_f32_16x16x32_bf16 v[16:19], v[156:159], v[232:235], v[16:19]
	v_mfma_f32_16x16x32_bf16 v[4:7], v[148:151], v[240:243], v[4:7]
	v_mfma_f32_16x16x32_bf16 v[0:3], v[156:159], v[240:243], v[0:3]
	s_setprio 0
	s_barrier
	s_cmp_gt_u32 s65, 13
	s_cbranch_scc0 .LBB0_699
	s_and_b64 vcc, exec, s[18:19]
	s_cbranch_vccz .LBB0_702
	s_barrier

; #define PG8_STAGE(bufoff, gbase, voff) do { _Pragma("unroll") for (int _i = 0; _i < 2; ++_i) \
;         __builtin_amdgcn_global_load_lds((const unsigned*)((const char*)(gbase) + (voff)[_i]), (PG8_LAS unsigned*)(lds + (bufoff) + ldsw + _i * 8192), 16, 0, 0); } while (0)
; #define PG8_LDA(dst, b, h) do { _Pragma("unroll") for (int m = 0; m < 4; ++m) _Pragma("unroll") for (int k = 0; k < 2; ++k) dst[m][k] = *(const PG8_LAS bf16x8*)(lds + PG8_SA(b, h) + aoff + m * 2048 + k * 1024); } while (0)
; #define PG8_LDB(dst, b, h) do { _Pragma("unroll") for (int n = 0; n < 2; ++n) _Pragma("unroll") for (int k = 0; k < 2; ++k) dst[n][k] = *(const PG8_LAS bf16x8*)(lds + PG8_SB(b, h) + boff + n * 2048 + k * 1024); } while (0)
; #define PG8_MMA(ai, bj, At, Bt) do { __builtin_amdgcn_s_setprio(1); _Pragma("unroll") for (int m = 0; m < 4; ++m) _Pragma("unroll") for (int n = 0; n < 2; ++n) _Pragma("unroll") for (int k = 0; k < 2; ++k) \
;         acc[ai][bj][m][n] = __builtin_amdgcn_mfma_f32_16x16x32_bf16(Bt[n][k], At[m][k], acc[ai][bj][m][n], 0, 0, 0); __builtin_amdgcn_s_setprio(0); } while (0)
; #define PG8_WAIT_V(n) asm volatile("s_waitcnt vmcnt(" #n ")" ::: "memory")
; #define PG8_WAIT_L(n) asm volatile("s_waitcnt lgkmcnt(" #n ")" ::: "memory")
; #define PG8_BAR __builtin_amdgcn_s_barrier()
; #define PG8_SCHED __builtin_amdgcn_sched_barrier(0)
; template <class Epi, class Sched, bool ALIGN_EPI = false, bool SP2 = false>
; __device__ __forceinline__ void gemm_phase(PG8_LAS unsigned char* lds, const Gemm g, const Sched& S, const Epi& E) {
;     ...
;             PG8_LDB(B0, 0, 0); PG8_LDB(B1, 0, 1); PG8_SCHED; PG8_LDA(At, 0, 0); PG8_STAGE(PG8_SA(1, 1), a1 + hstep, voffA);
;             PG8_WAIT_V(8); PG8_WAIT_L(0); PG8_BAR; PG8_MMA(0, 0, At, B0); PG8_MMA(0, 1, At, B1); PG8_BAR; PG8_SCHED;
;             PG8_LDA(At, 0, 1); PG8_STAGE(PG8_SB(0, 0), b2, voffB); PG8_STAGE(PG8_SB(0, 1), b2 + hstep, voffB); PG8_STAGE(PG8_SA(0, 0), a2, voffA);
;             PG8_WAIT_V(8); PG8_WAIT_L(0); PG8_BAR; PG8_MMA(1, 0, At, B0); PG8_MMA(1, 1, At, B1); PG8_BAR; PG8_SCHED;
.LBB0_826:
	ds_read_b128 v[154:157], v150
	ds_read_b128 v[158:161], v150 offset:1024
	ds_read_b128 v[162:165], v150 offset:2048
	ds_read_b128 v[170:173], v150 offset:3072
	ds_read_b128 v[174:177], v151
	ds_read_b128 v[178:181], v151 offset:1024
	ds_read_b128 v[182:185], v151 offset:2048
	ds_read_b128 v[186:189], v151 offset:3072
	s_add_u32 s22, s0, 0xfffc0080
	s_addc_u32 s23, s1, -1
	s_cmp_eq_u32 s44, 12
	s_cselect_b32 s25, s15, s23
	s_cselect_b32 s24, s40, s22
	s_cselect_b32 s23, s13, s43
	s_cselect_b32 s22, s41, s42
	v_lshl_add_u64 v[144:145], s[0:1], 0, v[136:137]
	s_add_i32 m0, s21, 0xc000
	ds_read_b128 v[190:193], v152
	ds_read_b128 v[194:197], v152 offset:1024
	ds_read_b128 v[204:207], v152 offset:2048
	ds_read_b128 v[208:211], v152 offset:3072
	ds_read_b128 v[212:215], v152 offset:4096
	ds_read_b128 v[216:219], v152 offset:5120
	ds_read_b128 v[220:223], v152 offset:6144
	ds_read_b128 v[224:227], v152 offset:7168
	global_load_lds_dwordx4 v[144:145], off
	v_lshl_add_u64 v[144:145], s[0:1], 0, v[138:139]
	s_add_i32 m0, s21, 0xe000
	s_nop 0
	global_load_lds_dwordx4 v[144:145], off
	s_waitcnt vmcnt(8)
	s_waitcnt lgkmcnt(0)
	s_barrier
	s_setprio 1
	s_waitcnt lgkmcnt(0)
	v_mfma_f32_16x16x32_bf16 v[124:127], v[154:157], v[190:193], v[124:127]
	v_mfma_f32_16x16x32_bf16 v[120:123], v[162:165], v[190:193], v[120:123]
	v_mfma_f32_16x16x32_bf16 v[108:111], v[154:157], v[204:207], v[108:111]
	v_mfma_f32_16x16x32_bf16 v[104:107], v[162:165], v[204:207], v[104:107]
	v_mfma_f32_16x16x32_bf16 v[92:95], v[154:157], v[212:215], v[92:95]
	v_mfma_f32_16x16x32_bf16 v[88:91], v[162:165], v[212:215], v[88:91]
	v_mfma_f32_16x16x32_bf16 v[76:79], v[154:157], v[220:223], v[76:79]
	v_mfma_f32_16x16x32_bf16 v[72:75], v[162:165], v[220:223], v[72:75]
	v_mfma_f32_16x16x32_bf16 v[124:127], v[158:161], v[194:197], v[124:127]
	v_mfma_f32_16x16x32_bf16 v[120:123], v[170:173], v[194:197], v[120:123]
	v_mfma_f32_16x16x32_bf16 v[108:111], v[158:161], v[208:211], v[108:111]
	v_mfma_f32_16x16x32_bf16 v[104:107], v[170:173], v[208:211], v[104:107]
	v_mfma_f32_16x16x32_bf16 v[92:95], v[158:161], v[216:219], v[92:95]
	v_mfma_f32_16x16x32_bf16 v[88:91], v[170:173], v[216:219], v[88:91]
	v_mfma_f32_16x16x32_bf16 v[76:79], v[158:161], v[224:227], v[76:79]
	v_mfma_f32_16x16x32_bf16 v[72:75], v[170:173], v[224:227], v[72:75]
	s_setprio 0
	s_setprio 1
	v_mfma_f32_16x16x32_bf16 v[116:119], v[174:177], v[190:193], v[116:119]
	v_mfma_f32_16x16x32_bf16 v[112:115], v[182:185], v[190:193], v[112:115]
	v_mfma_f32_16x16x32_bf16 v[100:103], v[174:177], v[204:207], v[100:103]
	v_mfma_f32_16x16x32_bf16 v[96:99], v[182:185], v[204:207], v[96:99]
	v_mfma_f32_16x16x32_bf16 v[84:87], v[174:177], v[212:215], v[84:87]
	v_mfma_f32_16x16x32_bf16 v[80:83], v[182:185], v[212:215], v[80:83]
	v_mfma_f32_16x16x32_bf16 v[68:71], v[174:177], v[220:223], v[68:71]
	v_mfma_f32_16x16x32_bf16 v[64:67], v[182:185], v[220:223], v[64:67]
	v_mfma_f32_16x16x32_bf16 v[116:119], v[178:181], v[194:197], v[116:119]
	v_mfma_f32_16x16x32_bf16 v[112:115], v[186:189], v[194:197], v[112:115]
	v_mfma_f32_16x16x32_bf16 v[100:103], v[178:181], v[208:211], v[100:103]
	v_mfma_f32_16x16x32_bf16 v[96:99], v[186:189], v[208:211], v[96:99]
	v_mfma_f32_16x16x32_bf16 v[84:87], v[178:181], v[216:219], v[84:87]
	v_mfma_f32_16x16x32_bf16 v[80:83], v[186:189], v[216:219], v[80:83]
	v_mfma_f32_16x16x32_bf16 v[68:71], v[178:181], v[224:227], v[68:71]
	v_mfma_f32_16x16x32_bf16 v[64:67], v[186:189], v[224:227], v[64:67]
	s_setprio 0
	s_barrier
	s_add_i32 s45, s46, s26
	v_lshl_add_u64 v[144:145], s[22:23], 0, v[132:133]
	s_mov_b32 m0, s45
	ds_read_b128 v[190:193], v152 offset:16384
	ds_read_b128 v[194:197], v152 offset:17408
	ds_read_b128 v[204:207], v152 offset:18432
	ds_read_b128 v[208:211], v152 offset:19456
	ds_read_b128 v[212:215], v152 offset:20480
	ds_read_b128 v[216:219], v152 offset:21504
	ds_read_b128 v[220:223], v152 offset:22528
	ds_read_b128 v[224:227], v152 offset:23552
	global_load_lds_dwordx4 v[144:145], off
	s_add_i32 m0, s45, 0x2000
	s_add_u32 s48, s22, 0x40000
	v_lshl_add_u64 v[166:167], s[22:23], 0, v[128:129]
	s_addc_u32 s49, s23, 0
	s_add_i32 s45, s38, s26
	global_load_lds_dwordx4 v[166:167], off
	v_lshl_add_u64 v[228:229], s[48:49], 0, v[132:133]
	s_mov_b32 m0, s45
	v_lshl_add_u64 v[230:231], s[24:25], 0, v[130:131]
	global_load_lds_dwordx4 v[228:229], off
	v_lshl_add_u64 v[228:229], s[48:49], 0, v[128:129]
	s_add_i32 m0, s45, 0x2000
	s_nop 0
	global_load_lds_dwordx4 v[228:229], off
	v_lshl_add_u64 v[228:229], s[24:25], 0, v[134:135]
	s_mov_b32 m0, s21
	s_nop 0
	global_load_lds_dwordx4 v[228:229], off
	s_mov_b32 m0, s29
	s_nop 0
	global_load_lds_dwordx4 v[230:231], off
	s_waitcnt vmcnt(8)
	s_waitcnt lgkmcnt(0)
	s_barrier
; #define PG8_STAGE(bufoff, gbase, voff) do { _Pragma("unroll") for (int _i = 0; _i < 2; ++_i) \
;         __builtin_amdgcn_global_load_lds((const unsigned*)((const char*)(gbase) + (voff)[_i]), (PG8_LAS unsigned*)(lds + (bufoff) + ldsw + _i * 8192), 16, 0, 0); } while (0)
; #define PG8_LDA(dst, b, h) do { _Pragma("unroll") for (int m = 0; m < 4; ++m) _Pragma("unroll") for (int k = 0; k < 2; ++k) dst[m][k] = *(const PG8_LAS bf16x8*)(lds + PG8_SA(b, h) + aoff + m * 2048 + k * 1024); } while (0)
; #define PG8_LDB(dst, b, h) do { _Pragma("unroll") for (int n = 0; n < 2; ++n) _Pragma("unroll") for (int k = 0; k < 2; ++k) dst[n][k] = *(const PG8_LAS bf16x8*)(lds + PG8_SB(b, h) + boff + n * 2048 + k * 1024); } while (0)
; #define PG8_MMA(ai, bj, At, Bt) do { __builtin_amdgcn_s_setprio(1); _Pragma("unroll") for (int m = 0; m < 4; ++m) _Pragma("unroll") for (int n = 0; n < 2; ++n) _Pragma("unroll") for (int k = 0; k < 2; ++k) \
;         acc[ai][bj][m][n] = __builtin_amdgcn_mfma_f32_16x16x32_bf16(Bt[n][k], At[m][k], acc[ai][bj][m][n], 0, 0, 0); __builtin_amdgcn_s_setprio(0); } while (0)
; #define PG8_WAIT_V(n) asm volatile("s_waitcnt vmcnt(" #n ")" ::: "memory")
; #define PG8_WAIT_L(n) asm volatile("s_waitcnt lgkmcnt(" #n ")" ::: "memory")
; #define PG8_BAR __builtin_amdgcn_s_barrier()
; #define PG8_SCHED __builtin_amdgcn_sched_barrier(0)
; template <class Epi, class Sched, bool ALIGN_EPI = false, bool SP2 = false>
; __device__ __forceinline__ void gemm_phase(PG8_LAS unsigned char* lds, const Gemm g, const Sched& S, const Epi& E) {
;     ...
;             PG8_WAIT_V(8); PG8_WAIT_L(0); PG8_BAR; PG8_MMA(1, 0, At, B0); PG8_MMA(1, 1, At, B1); PG8_BAR; PG8_SCHED;
;             PG8_LDB(B0, 1, 0); PG8_LDB(B1, 1, 1); PG8_SCHED; PG8_LDA(At, 1, 0); PG8_STAGE(PG8_SA(0, 1), a2 + hstep, voffA);
;             PG8_WAIT_V(8); PG8_WAIT_L(0); PG8_BAR; PG8_MMA(0, 0, At, B0); PG8_MMA(0, 1, At, B1); PG8_BAR; PG8_SCHED;
	s_setprio 1
	s_waitcnt lgkmcnt(0)
	v_mfma_f32_16x16x32_bf16 v[60:63], v[154:157], v[190:193], v[60:63]
	v_mfma_f32_16x16x32_bf16 v[56:59], v[162:165], v[190:193], v[56:59]
	v_mfma_f32_16x16x32_bf16 v[44:47], v[154:157], v[204:207], v[44:47]
	v_mfma_f32_16x16x32_bf16 v[40:43], v[162:165], v[204:207], v[40:43]
	v_mfma_f32_16x16x32_bf16 v[28:31], v[154:157], v[212:215], v[28:31]
	v_mfma_f32_16x16x32_bf16 v[24:27], v[162:165], v[212:215], v[24:27]
	v_mfma_f32_16x16x32_bf16 v[12:15], v[154:157], v[220:223], v[12:15]
	v_mfma_f32_16x16x32_bf16 v[8:11], v[162:165], v[220:223], v[8:11]
	v_mfma_f32_16x16x32_bf16 v[60:63], v[158:161], v[194:197], v[60:63]
	v_mfma_f32_16x16x32_bf16 v[56:59], v[170:173], v[194:197], v[56:59]
	v_mfma_f32_16x16x32_bf16 v[44:47], v[158:161], v[208:211], v[44:47]
	v_mfma_f32_16x16x32_bf16 v[40:43], v[170:173], v[208:211], v[40:43]
	v_mfma_f32_16x16x32_bf16 v[28:31], v[158:161], v[216:219], v[28:31]
	v_mfma_f32_16x16x32_bf16 v[24:27], v[170:173], v[216:219], v[24:27]
	v_mfma_f32_16x16x32_bf16 v[12:15], v[158:161], v[224:227], v[12:15]
	v_mfma_f32_16x16x32_bf16 v[8:11], v[170:173], v[224:227], v[8:11]
	s_setprio 0
	s_setprio 1
	v_mfma_f32_16x16x32_bf16 v[52:55], v[174:177], v[190:193], v[52:55]
	v_mfma_f32_16x16x32_bf16 v[48:51], v[182:185], v[190:193], v[48:51]
	v_mfma_f32_16x16x32_bf16 v[36:39], v[174:177], v[204:207], v[36:39]
	v_mfma_f32_16x16x32_bf16 v[32:35], v[182:185], v[204:207], v[32:35]
	v_mfma_f32_16x16x32_bf16 v[20:23], v[174:177], v[212:215], v[20:23]
	v_mfma_f32_16x16x32_bf16 v[16:19], v[182:185], v[212:215], v[16:19]
	v_mfma_f32_16x16x32_bf16 v[4:7], v[174:177], v[220:223], v[4:7]
	v_mfma_f32_16x16x32_bf16 v[0:3], v[182:185], v[220:223], v[0:3]
	v_mfma_f32_16x16x32_bf16 v[52:55], v[178:181], v[194:197], v[52:55]
	v_mfma_f32_16x16x32_bf16 v[48:51], v[186:189], v[194:197], v[48:51]
	v_mfma_f32_16x16x32_bf16 v[36:39], v[178:181], v[208:211], v[36:39]
	v_mfma_f32_16x16x32_bf16 v[32:35], v[186:189], v[208:211], v[32:35]
	v_mfma_f32_16x16x32_bf16 v[20:23], v[178:181], v[216:219], v[20:23]
	v_mfma_f32_16x16x32_bf16 v[16:19], v[186:189], v[216:219], v[16:19]
	v_mfma_f32_16x16x32_bf16 v[4:7], v[178:181], v[224:227], v[4:7]
	v_mfma_f32_16x16x32_bf16 v[0:3], v[186:189], v[224:227], v[0:3]
	s_setprio 0
	s_barrier
	s_add_i32 s45, 0, 0x18000
	v_add_u32_e32 v153, s45, v147
	s_add_i32 s47, 0, 0x1c000
	ds_read_b128 v[154:157], v153
	ds_read_b128 v[158:161], v153 offset:1024
	ds_read_b128 v[162:165], v153 offset:2048
	ds_read_b128 v[170:173], v153 offset:3072
	v_add_u32_e32 v153, s47, v147
	ds_read_b128 v[174:177], v153
	ds_read_b128 v[178:181], v153 offset:1024
	ds_read_b128 v[182:185], v153 offset:2048
	ds_read_b128 v[186:189], v153 offset:3072
	s_add_u32 s24, s24, 0x40000
	s_addc_u32 s25, s25, 0
	s_mov_b32 m0, s30
	v_lshl_add_u64 v[232:233], s[24:25], 0, v[134:135]
	ds_read_b128 v[190:193], v152 offset:32768
	ds_read_b128 v[194:197], v152 offset:33792
	ds_read_b128 v[204:207], v152 offset:34816
	ds_read_b128 v[208:211], v152 offset:35840
	ds_read_b128 v[212:215], v152 offset:36864
	ds_read_b128 v[216:219], v152 offset:37888
	ds_read_b128 v[220:223], v152 offset:38912
	ds_read_b128 v[224:227], v152 offset:39936
	global_load_lds_dwordx4 v[232:233], off
	v_lshl_add_u64 v[232:233], s[24:25], 0, v[130:131]
	s_mov_b32 m0, s31
	s_nop 0
	global_load_lds_dwordx4 v[232:233], off
	s_waitcnt vmcnt(8)
	s_waitcnt lgkmcnt(0)
	s_barrier
	s_setprio 1
	s_waitcnt lgkmcnt(0)
	v_mfma_f32_16x16x32_bf16 v[124:127], v[154:157], v[190:193], v[124:127]
	v_mfma_f32_16x16x32_bf16 v[120:123], v[162:165], v[190:193], v[120:123]
	v_mfma_f32_16x16x32_bf16 v[108:111], v[154:157], v[204:207], v[108:111]
	v_mfma_f32_16x16x32_bf16 v[104:107], v[162:165], v[204:207], v[104:107]
	v_mfma_f32_16x16x32_bf16 v[92:95], v[154:157], v[212:215], v[92:95]
	v_mfma_f32_16x16x32_bf16 v[88:91], v[162:165], v[212:215], v[88:91]
	v_mfma_f32_16x16x32_bf16 v[76:79], v[154:157], v[220:223], v[76:79]
	v_mfma_f32_16x16x32_bf16 v[72:75], v[162:165], v[220:223], v[72:75]
	v_mfma_f32_16x16x32_bf16 v[124:127], v[158:161], v[194:197], v[124:127]
	v_mfma_f32_16x16x32_bf16 v[120:123], v[170:173], v[194:197], v[120:123]
	v_mfma_f32_16x16x32_bf16 v[108:111], v[158:161], v[208:211], v[108:111]
	v_mfma_f32_16x16x32_bf16 v[104:107], v[170:173], v[208:211], v[104:107]
	v_mfma_f32_16x16x32_bf16 v[92:95], v[158:161], v[216:219], v[92:95]
	v_mfma_f32_16x16x32_bf16 v[88:91], v[170:173], v[216:219], v[88:91]
	v_mfma_f32_16x16x32_bf16 v[76:79], v[158:161], v[224:227], v[76:79]
	v_mfma_f32_16x16x32_bf16 v[72:75], v[170:173], v[224:227], v[72:75]
	s_setprio 0
	s_setprio 1
	v_mfma_f32_16x16x32_bf16 v[116:119], v[174:177], v[190:193], v[116:119]
	v_mfma_f32_16x16x32_bf16 v[112:115], v[182:185], v[190:193], v[112:115]
	v_mfma_f32_16x16x32_bf16 v[100:103], v[174:177], v[204:207], v[100:103]
	v_mfma_f32_16x16x32_bf16 v[96:99], v[182:185], v[204:207], v[96:99]
	v_mfma_f32_16x16x32_bf16 v[84:87], v[174:177], v[212:215], v[84:87]
	v_mfma_f32_16x16x32_bf16 v[80:83], v[182:185], v[212:215], v[80:83]
	v_mfma_f32_16x16x32_bf16 v[68:71], v[174:177], v[220:223], v[68:71]
	v_mfma_f32_16x16x32_bf16 v[64:67], v[182:185], v[220:223], v[64:67]
	v_mfma_f32_16x16x32_bf16 v[116:119], v[178:181], v[194:197], v[116:119]
	v_mfma_f32_16x16x32_bf16 v[112:115], v[186:189], v[194:197], v[112:115]
	v_mfma_f32_16x16x32_bf16 v[100:103], v[178:181], v[208:211], v[100:103]
	v_mfma_f32_16x16x32_bf16 v[96:99], v[186:189], v[208:211], v[96:99]
	v_mfma_f32_16x16x32_bf16 v[84:87], v[178:181], v[216:219], v[84:87]
	v_mfma_f32_16x16x32_bf16 v[80:83], v[186:189], v[216:219], v[80:83]
	v_mfma_f32_16x16x32_bf16 v[68:71], v[178:181], v[224:227], v[68:71]
	v_mfma_f32_16x16x32_bf16 v[64:67], v[186:189], v[224:227], v[64:67]
	s_setprio 0
	s_barrier
; #define PG8_STAGE(bufoff, gbase, voff) do { _Pragma("unroll") for (int _i = 0; _i < 2; ++_i) \
;         __builtin_amdgcn_global_load_lds((const unsigned*)((const char*)(gbase) + (voff)[_i]), (PG8_LAS unsigned*)(lds + (bufoff) + ldsw + _i * 8192), 16, 0, 0); } while (0)
; #define PG8_LDA(dst, b, h) do { _Pragma("unroll") for (int m = 0; m < 4; ++m) _Pragma("unroll") for (int k = 0; k < 2; ++k) dst[m][k] = *(const PG8_LAS bf16x8*)(lds + PG8_SA(b, h) + aoff + m * 2048 + k * 1024); } while (0)
; #define PG8_MMA(ai, bj, At, Bt) do { __builtin_amdgcn_s_setprio(1); _Pragma("unroll") for (int m = 0; m < 4; ++m) _Pragma("unroll") for (int n = 0; n < 2; ++n) _Pragma("unroll") for (int k = 0; k < 2; ++k) \
;         acc[ai][bj][m][n] = __builtin_amdgcn_mfma_f32_16x16x32_bf16(Bt[n][k], At[m][k], acc[ai][bj][m][n], 0, 0, 0); __builtin_amdgcn_s_setprio(0); } while (0)
; #define PG8_WAIT_V(n) asm volatile("s_waitcnt vmcnt(" #n ")" ::: "memory")
; #define PG8_WAIT_L(n) asm volatile("s_waitcnt lgkmcnt(" #n ")" ::: "memory")
; #define PG8_BAR __builtin_amdgcn_s_barrier()
; #define PG8_SCHED __builtin_amdgcn_sched_barrier(0)
; template <class Epi, class Sched, bool ALIGN_EPI = false, bool SP2 = false>
; __device__ __forceinline__ void gemm_phase(PG8_LAS unsigned char* lds, const Gemm g, const Sched& S, const Epi& E) {
;     ...
;             PG8_LDA(At, 1, 1); PG8_STAGE(PG8_SB(1, 0), b3, voffB); PG8_STAGE(PG8_SB(1, 1), b3 + hstep, voffB); PG8_STAGE(PG8_SA(1, 0), a3, voffA);
;             PG8_WAIT_V(8); PG8_WAIT_L(0); PG8_BAR; PG8_MMA(1, 0, At, B0); PG8_MMA(1, 1, At, B1); PG8_BAR; PG8_SCHED;
	s_add_i32 s24, s45, s26
	v_lshl_add_u64 v[144:145], v[144:145], 0, s[8:9]
	s_mov_b32 m0, s24
	ds_read_b128 v[190:193], v152 offset:49152
	ds_read_b128 v[194:197], v152 offset:50176
	ds_read_b128 v[204:207], v152 offset:51200
	ds_read_b128 v[208:211], v152 offset:52224
	ds_read_b128 v[212:215], v152 offset:53248
	ds_read_b128 v[216:219], v152 offset:54272
	ds_read_b128 v[220:223], v152 offset:55296
	ds_read_b128 v[224:227], v152 offset:56320
	global_load_lds_dwordx4 v[144:145], off
	s_add_i32 m0, s24, 0x2000
	s_add_u32 s22, s22, 0x40080
	v_lshl_add_u64 v[144:145], v[166:167], 0, s[8:9]
	s_addc_u32 s23, s23, 0
	s_add_i32 s24, s47, s26
	global_load_lds_dwordx4 v[144:145], off
	v_lshl_add_u64 v[144:145], s[22:23], 0, v[132:133]
	s_mov_b32 m0, s24
	s_nop 0
	global_load_lds_dwordx4 v[144:145], off
	v_lshl_add_u64 v[144:145], s[22:23], 0, v[128:129]
	s_add_i32 m0, s24, 0x2000
	s_nop 0
	global_load_lds_dwordx4 v[144:145], off
	v_lshl_add_u64 v[144:145], v[228:229], 0, s[8:9]
	s_mov_b32 m0, s35
	s_nop 0
	global_load_lds_dwordx4 v[144:145], off
	v_lshl_add_u64 v[144:145], v[230:231], 0, s[8:9]
	s_mov_b32 m0, s36
	s_nop 0
	global_load_lds_dwordx4 v[144:145], off
	s_waitcnt vmcnt(8)
	s_waitcnt lgkmcnt(0)
	s_barrier
	s_setprio 1
	s_waitcnt lgkmcnt(0)
	v_mfma_f32_16x16x32_bf16 v[60:63], v[154:157], v[190:193], v[60:63]
	v_mfma_f32_16x16x32_bf16 v[56:59], v[162:165], v[190:193], v[56:59]
	v_mfma_f32_16x16x32_bf16 v[44:47], v[154:157], v[204:207], v[44:47]
	v_mfma_f32_16x16x32_bf16 v[40:43], v[162:165], v[204:207], v[40:43]
	v_mfma_f32_16x16x32_bf16 v[28:31], v[154:157], v[212:215], v[28:31]
	v_mfma_f32_16x16x32_bf16 v[24:27], v[162:165], v[212:215], v[24:27]
	v_mfma_f32_16x16x32_bf16 v[12:15], v[154:157], v[220:223], v[12:15]
	v_mfma_f32_16x16x32_bf16 v[8:11], v[162:165], v[220:223], v[8:11]
	v_mfma_f32_16x16x32_bf16 v[60:63], v[158:161], v[194:197], v[60:63]
	v_mfma_f32_16x16x32_bf16 v[56:59], v[170:173], v[194:197], v[56:59]
	v_mfma_f32_16x16x32_bf16 v[44:47], v[158:161], v[208:211], v[44:47]
	v_mfma_f32_16x16x32_bf16 v[40:43], v[170:173], v[208:211], v[40:43]
	v_mfma_f32_16x16x32_bf16 v[28:31], v[158:161], v[216:219], v[28:31]
	v_mfma_f32_16x16x32_bf16 v[24:27], v[170:173], v[216:219], v[24:27]
	v_mfma_f32_16x16x32_bf16 v[12:15], v[158:161], v[224:227], v[12:15]
	v_mfma_f32_16x16x32_bf16 v[8:11], v[170:173], v[224:227], v[8:11]
	s_setprio 0
	s_setprio 1
	v_mfma_f32_16x16x32_bf16 v[52:55], v[174:177], v[190:193], v[52:55]
	s_add_i32 s44, s44, 2
	s_add_u32 s0, s0, 0x100
	s_addc_u32 s1, s1, 0
	s_add_u32 s42, s42, 0x100
	s_addc_u32 s43, s43, 0
	v_mfma_f32_16x16x32_bf16 v[48:51], v[182:185], v[190:193], v[48:51]
	v_mfma_f32_16x16x32_bf16 v[36:39], v[174:177], v[204:207], v[36:39]
	v_mfma_f32_16x16x32_bf16 v[32:35], v[182:185], v[204:207], v[32:35]
	v_mfma_f32_16x16x32_bf16 v[20:23], v[174:177], v[212:215], v[20:23]
	v_mfma_f32_16x16x32_bf16 v[16:19], v[182:185], v[212:215], v[16:19]
	v_mfma_f32_16x16x32_bf16 v[4:7], v[174:177], v[220:223], v[4:7]
	v_mfma_f32_16x16x32_bf16 v[0:3], v[182:185], v[220:223], v[0:3]
	v_mfma_f32_16x16x32_bf16 v[52:55], v[178:181], v[194:197], v[52:55]
	v_mfma_f32_16x16x32_bf16 v[48:51], v[186:189], v[194:197], v[48:51]
	v_mfma_f32_16x16x32_bf16 v[36:39], v[178:181], v[208:211], v[36:39]
	v_mfma_f32_16x16x32_bf16 v[32:35], v[186:189], v[208:211], v[32:35]
	v_mfma_f32_16x16x32_bf16 v[20:23], v[178:181], v[216:219], v[20:23]
	v_mfma_f32_16x16x32_bf16 v[16:19], v[186:189], v[216:219], v[16:19]
	v_mfma_f32_16x16x32_bf16 v[4:7], v[178:181], v[224:227], v[4:7]
	v_mfma_f32_16x16x32_bf16 v[0:3], v[186:189], v[224:227], v[0:3]
	s_setprio 0
	s_barrier
	s_cmp_gt_u32 s44, 13
	s_cbranch_scc0 .LBB0_826
	s_and_b64 vcc, exec, s[10:11]
	s_cbranch_vccz .LBB0_829
	s_barrier

; #define PG8_STAGE(bufoff, gbase, voff) do { _Pragma("unroll") for (int _i = 0; _i < 2; ++_i) \
;         __builtin_amdgcn_global_load_lds((const unsigned*)((const char*)(gbase) + (voff)[_i]), (PG8_LAS unsigned*)(lds + (bufoff) + ldsw + _i * 8192), 16, 0, 0); } while (0)
; #define PG8_LDA(dst, b, h) do { _Pragma("unroll") for (int m = 0; m < 4; ++m) _Pragma("unroll") for (int k = 0; k < 2; ++k) dst[m][k] = *(const PG8_LAS bf16x8*)(lds + PG8_SA(b, h) + aoff + m * 2048 + k * 1024); } while (0)
; #define PG8_LDB(dst, b, h) do { _Pragma("unroll") for (int n = 0; n < 2; ++n) _Pragma("unroll") for (int k = 0; k < 2; ++k) dst[n][k] = *(const PG8_LAS bf16x8*)(lds + PG8_SB(b, h) + boff + n * 2048 + k * 1024); } while (0)
; #define PG8_MMA(ai, bj, At, Bt) do { __builtin_amdgcn_s_setprio(1); _Pragma("unroll") for (int m = 0; m < 4; ++m) _Pragma("unroll") for (int n = 0; n < 2; ++n) _Pragma("unroll") for (int k = 0; k < 2; ++k) \
;         acc[ai][bj][m][n] = __builtin_amdgcn_mfma_f32_16x16x32_bf16(Bt[n][k], At[m][k], acc[ai][bj][m][n], 0, 0, 0); __builtin_amdgcn_s_setprio(0); } while (0)
; #define PG8_WAIT_V(n) asm volatile("s_waitcnt vmcnt(" #n ")" ::: "memory")
; #define PG8_WAIT_L(n) asm volatile("s_waitcnt lgkmcnt(" #n ")" ::: "memory")
; #define PG8_BAR __builtin_amdgcn_s_barrier()
; template <class Epi, class Sched, bool ALIGN_EPI = false, bool SP2 = false>
; __device__ __forceinline__ void gemm_phase(PG8_LAS unsigned char* lds, const Gemm g, const Sched& S, const Epi& E) {
;     ...
;             const char* a1 = cA + (size_t)(t + 1) * kstep;
;             const char* a2 = last ? nA : cA + (size_t)(t + 2) * kstep; const char* b2 = last ? nB : cB + (size_t)(t + 2) * kstep;
;             const char* a3 = a2 + kstep; const char* b3 = b2 + kstep;
;             if (last && has_next) S.a_ready(nxt);
;             if constexpr (SP2) {
;             PG8_LDB(B0, 0, 0); PG8_LDB(B1, 0, 1); PG8_SCHED; PG8_LDA(At, 0, 0); PG8_STAGE(PG8_SA(1, 1), a1 + hstep, voffA);
;             PG8_WAIT_V(8); PG8_WAIT_L(0); PG8_BAR; PG8_MMA(0, 0, At, B0); PG8_MMA(0, 1, At, B1); PG8_BAR; PG8_SCHED;
;             PG8_LDA(At, 0, 1); PG8_STAGE(PG8_SB(0, 0), b2, voffB); PG8_STAGE(PG8_SB(0, 1), b2 + hstep, voffB); PG8_STAGE(PG8_SA(0, 0), a2, voffA);
;             PG8_WAIT_V(8); PG8_WAIT_L(0); PG8_BAR; PG8_MMA(1, 0, At, B0); PG8_MMA(1, 1, At, B1); PG8_BAR; PG8_SCHED;
.LBB0_908:
	ds_read_b128 v[128:131], v189
	ds_read_b128 v[132:135], v189 offset:1024
	ds_read_b128 v[136:139], v189 offset:2048
	ds_read_b128 v[140:143], v189 offset:3072
	ds_read_b128 v[144:147], v190
	ds_read_b128 v[148:151], v190 offset:1024
	ds_read_b128 v[152:155], v190 offset:2048
	ds_read_b128 v[156:159], v190 offset:3072
	s_add_u32 s24, s22, 0x100
	s_addc_u32 s25, s23, 0
	s_cmp_eq_u32 s65, 40
	s_cselect_b32 s29, s9, s25
	s_cselect_b32 s28, s8, s24
	s_cselect_b32 s27, s21, s63
	s_cselect_b32 s26, s20, s62
	v_lshl_add_u64 v[182:183], s[22:23], 0, v[170:171]
	s_add_i32 m0, s31, 0xc000
	ds_read_b128 v[178:181], v191
	ds_read_b128 v[196:199], v191 offset:1024
	ds_read_b128 v[204:207], v191 offset:2048
	ds_read_b128 v[208:211], v191 offset:3072
	ds_read_b128 v[212:215], v191 offset:4096
	ds_read_b128 v[216:219], v191 offset:5120
	ds_read_b128 v[220:223], v191 offset:6144
	ds_read_b128 v[224:227], v191 offset:7168
	global_load_lds_dwordx4 v[182:183], off
	v_lshl_add_u64 v[182:183], s[22:23], 0, v[172:173]
	s_add_i32 m0, s31, 0xe000
	s_nop 0
	global_load_lds_dwordx4 v[182:183], off
	s_waitcnt vmcnt(8)
	s_waitcnt lgkmcnt(0)
	s_barrier
	s_setprio 1
	s_waitcnt lgkmcnt(0)
	v_mfma_f32_16x16x32_bf16 v[124:127], v[128:131], v[178:181], v[124:127]
	v_mfma_f32_16x16x32_bf16 v[120:123], v[136:139], v[178:181], v[120:123]
	v_mfma_f32_16x16x32_bf16 v[108:111], v[128:131], v[204:207], v[108:111]
	v_mfma_f32_16x16x32_bf16 v[104:107], v[136:139], v[204:207], v[104:107]
	v_mfma_f32_16x16x32_bf16 v[92:95], v[128:131], v[212:215], v[92:95]
	v_mfma_f32_16x16x32_bf16 v[88:91], v[136:139], v[212:215], v[88:91]
	v_mfma_f32_16x16x32_bf16 v[76:79], v[128:131], v[220:223], v[76:79]
	v_mfma_f32_16x16x32_bf16 v[72:75], v[136:139], v[220:223], v[72:75]
	v_mfma_f32_16x16x32_bf16 v[124:127], v[132:135], v[196:199], v[124:127]
	v_mfma_f32_16x16x32_bf16 v[120:123], v[140:143], v[196:199], v[120:123]
	v_mfma_f32_16x16x32_bf16 v[108:111], v[132:135], v[208:211], v[108:111]
	v_mfma_f32_16x16x32_bf16 v[104:107], v[140:143], v[208:211], v[104:107]
	v_mfma_f32_16x16x32_bf16 v[92:95], v[132:135], v[216:219], v[92:95]
	v_mfma_f32_16x16x32_bf16 v[88:91], v[140:143], v[216:219], v[88:91]
	v_mfma_f32_16x16x32_bf16 v[76:79], v[132:135], v[224:227], v[76:79]
	v_mfma_f32_16x16x32_bf16 v[72:75], v[140:143], v[224:227], v[72:75]
	s_setprio 0
	s_setprio 1
	v_mfma_f32_16x16x32_bf16 v[116:119], v[144:147], v[178:181], v[116:119]
	v_mfma_f32_16x16x32_bf16 v[112:115], v[152:155], v[178:181], v[112:115]
	v_mfma_f32_16x16x32_bf16 v[100:103], v[144:147], v[204:207], v[100:103]
	v_mfma_f32_16x16x32_bf16 v[96:99], v[152:155], v[204:207], v[96:99]
	v_mfma_f32_16x16x32_bf16 v[84:87], v[144:147], v[212:215], v[84:87]
	v_mfma_f32_16x16x32_bf16 v[80:83], v[152:155], v[212:215], v[80:83]
	v_mfma_f32_16x16x32_bf16 v[68:71], v[144:147], v[220:223], v[68:71]
	v_mfma_f32_16x16x32_bf16 v[64:67], v[152:155], v[220:223], v[64:67]
	v_mfma_f32_16x16x32_bf16 v[116:119], v[148:151], v[196:199], v[116:119]
	v_mfma_f32_16x16x32_bf16 v[112:115], v[156:159], v[196:199], v[112:115]
	v_mfma_f32_16x16x32_bf16 v[100:103], v[148:151], v[208:211], v[100:103]
	v_mfma_f32_16x16x32_bf16 v[96:99], v[156:159], v[208:211], v[96:99]
	v_mfma_f32_16x16x32_bf16 v[84:87], v[148:151], v[216:219], v[84:87]
	v_mfma_f32_16x16x32_bf16 v[80:83], v[156:159], v[216:219], v[80:83]
	v_mfma_f32_16x16x32_bf16 v[68:71], v[148:151], v[224:227], v[68:71]
	v_mfma_f32_16x16x32_bf16 v[64:67], v[156:159], v[224:227], v[64:67]
	s_setprio 0
	s_barrier
	s_add_i32 s22, s46, s30
	v_lshl_add_u64 v[182:183], s[26:27], 0, v[162:163]
	s_mov_b32 m0, s22
	ds_read_b128 v[178:181], v191 offset:16384
	ds_read_b128 v[196:199], v191 offset:17408
	ds_read_b128 v[204:207], v191 offset:18432
	ds_read_b128 v[208:211], v191 offset:19456
	ds_read_b128 v[212:215], v191 offset:20480
	ds_read_b128 v[216:219], v191 offset:21504
	ds_read_b128 v[220:223], v191 offset:22528
	ds_read_b128 v[224:227], v191 offset:23552
	global_load_lds_dwordx4 v[182:183], off
	s_add_i32 m0, s22, 0x2000
	s_add_u32 s22, s26, 0xb0000
	v_lshl_add_u64 v[200:201], s[26:27], 0, v[166:167]
	s_addc_u32 s23, s27, 0
	s_add_i32 s66, s47, s30
	global_load_lds_dwordx4 v[200:201], off
	v_lshl_add_u64 v[228:229], s[22:23], 0, v[162:163]
	s_mov_b32 m0, s66
	v_lshl_add_u64 v[230:231], s[28:29], 0, v[164:165]
	global_load_lds_dwordx4 v[228:229], off
	v_lshl_add_u64 v[228:229], s[22:23], 0, v[166:167]
	s_add_i32 m0, s66, 0x2000
	s_nop 0
	global_load_lds_dwordx4 v[228:229], off
	v_lshl_add_u64 v[228:229], s[28:29], 0, v[160:161]
	s_mov_b32 m0, s31
	s_nop 0
	global_load_lds_dwordx4 v[228:229], off
	s_mov_b32 m0, s33
	s_nop 0
	global_load_lds_dwordx4 v[230:231], off
	s_waitcnt vmcnt(8)
	s_waitcnt lgkmcnt(0)
	s_barrier
; #define PG8_STAGE(bufoff, gbase, voff) do { _Pragma("unroll") for (int _i = 0; _i < 2; ++_i) \
;         __builtin_amdgcn_global_load_lds((const unsigned*)((const char*)(gbase) + (voff)[_i]), (PG8_LAS unsigned*)(lds + (bufoff) + ldsw + _i * 8192), 16, 0, 0); } while (0)
; #define PG8_LDA(dst, b, h) do { _Pragma("unroll") for (int m = 0; m < 4; ++m) _Pragma("unroll") for (int k = 0; k < 2; ++k) dst[m][k] = *(const PG8_LAS bf16x8*)(lds + PG8_SA(b, h) + aoff + m * 2048 + k * 1024); } while (0)
; #define PG8_LDB(dst, b, h) do { _Pragma("unroll") for (int n = 0; n < 2; ++n) _Pragma("unroll") for (int k = 0; k < 2; ++k) dst[n][k] = *(const PG8_LAS bf16x8*)(lds + PG8_SB(b, h) + boff + n * 2048 + k * 1024); } while (0)
; #define PG8_MMA(ai, bj, At, Bt) do { __builtin_amdgcn_s_setprio(1); _Pragma("unroll") for (int m = 0; m < 4; ++m) _Pragma("unroll") for (int n = 0; n < 2; ++n) _Pragma("unroll") for (int k = 0; k < 2; ++k) \
;         acc[ai][bj][m][n] = __builtin_amdgcn_mfma_f32_16x16x32_bf16(Bt[n][k], At[m][k], acc[ai][bj][m][n], 0, 0, 0); __builtin_amdgcn_s_setprio(0); } while (0)
; #define PG8_WAIT_V(n) asm volatile("s_waitcnt vmcnt(" #n ")" ::: "memory")
; #define PG8_WAIT_L(n) asm volatile("s_waitcnt lgkmcnt(" #n ")" ::: "memory")
; #define PG8_BAR __builtin_amdgcn_s_barrier()
; #define PG8_SCHED __builtin_amdgcn_sched_barrier(0)
; template <class Epi, class Sched, bool ALIGN_EPI = false, bool SP2 = false>
; __device__ __forceinline__ void gemm_phase(PG8_LAS unsigned char* lds, const Gemm g, const Sched& S, const Epi& E) {
;     ...
;             PG8_WAIT_V(8); PG8_WAIT_L(0); PG8_BAR; PG8_MMA(1, 0, At, B0); PG8_MMA(1, 1, At, B1); PG8_BAR; PG8_SCHED;
;             PG8_LDB(B0, 1, 0); PG8_LDB(B1, 1, 1); PG8_SCHED; PG8_LDA(At, 1, 0); PG8_STAGE(PG8_SA(0, 1), a2 + hstep, voffA);
;             PG8_WAIT_V(8); PG8_WAIT_L(0); PG8_BAR; PG8_MMA(0, 0, At, B0); PG8_MMA(0, 1, At, B1); PG8_BAR; PG8_SCHED;
	s_setprio 1
	s_waitcnt lgkmcnt(0)
	v_mfma_f32_16x16x32_bf16 v[60:63], v[128:131], v[178:181], v[60:63]
	v_mfma_f32_16x16x32_bf16 v[56:59], v[136:139], v[178:181], v[56:59]
	v_mfma_f32_16x16x32_bf16 v[44:47], v[128:131], v[204:207], v[44:47]
	v_mfma_f32_16x16x32_bf16 v[40:43], v[136:139], v[204:207], v[40:43]
	v_mfma_f32_16x16x32_bf16 v[28:31], v[128:131], v[212:215], v[28:31]
	v_mfma_f32_16x16x32_bf16 v[24:27], v[136:139], v[212:215], v[24:27]
	v_mfma_f32_16x16x32_bf16 v[12:15], v[128:131], v[220:223], v[12:15]
	v_mfma_f32_16x16x32_bf16 v[8:11], v[136:139], v[220:223], v[8:11]
	v_mfma_f32_16x16x32_bf16 v[60:63], v[132:135], v[196:199], v[60:63]
	v_mfma_f32_16x16x32_bf16 v[56:59], v[140:143], v[196:199], v[56:59]
	v_mfma_f32_16x16x32_bf16 v[44:47], v[132:135], v[208:211], v[44:47]
	v_mfma_f32_16x16x32_bf16 v[40:43], v[140:143], v[208:211], v[40:43]
	v_mfma_f32_16x16x32_bf16 v[28:31], v[132:135], v[216:219], v[28:31]
	v_mfma_f32_16x16x32_bf16 v[24:27], v[140:143], v[216:219], v[24:27]
	v_mfma_f32_16x16x32_bf16 v[12:15], v[132:135], v[224:227], v[12:15]
	v_mfma_f32_16x16x32_bf16 v[8:11], v[140:143], v[224:227], v[8:11]
	s_setprio 0
	s_setprio 1
	v_mfma_f32_16x16x32_bf16 v[52:55], v[144:147], v[178:181], v[52:55]
	v_mfma_f32_16x16x32_bf16 v[48:51], v[152:155], v[178:181], v[48:51]
	v_mfma_f32_16x16x32_bf16 v[36:39], v[144:147], v[204:207], v[36:39]
	v_mfma_f32_16x16x32_bf16 v[32:35], v[152:155], v[204:207], v[32:35]
	v_mfma_f32_16x16x32_bf16 v[20:23], v[144:147], v[212:215], v[20:23]
	v_mfma_f32_16x16x32_bf16 v[16:19], v[152:155], v[212:215], v[16:19]
	v_mfma_f32_16x16x32_bf16 v[4:7], v[144:147], v[220:223], v[4:7]
	v_mfma_f32_16x16x32_bf16 v[0:3], v[152:155], v[220:223], v[0:3]
	v_mfma_f32_16x16x32_bf16 v[52:55], v[148:151], v[196:199], v[52:55]
	v_mfma_f32_16x16x32_bf16 v[48:51], v[156:159], v[196:199], v[48:51]
	v_mfma_f32_16x16x32_bf16 v[36:39], v[148:151], v[208:211], v[36:39]
	v_mfma_f32_16x16x32_bf16 v[32:35], v[156:159], v[208:211], v[32:35]
	v_mfma_f32_16x16x32_bf16 v[20:23], v[148:151], v[216:219], v[20:23]
	v_mfma_f32_16x16x32_bf16 v[16:19], v[156:159], v[216:219], v[16:19]
	v_mfma_f32_16x16x32_bf16 v[4:7], v[148:151], v[224:227], v[4:7]
	v_mfma_f32_16x16x32_bf16 v[0:3], v[156:159], v[224:227], v[0:3]
	s_setprio 0
	s_barrier
	s_add_i32 s66, 0, 0x18000
	s_add_i32 s67, 0, 0x1c000
	v_add_u32_e32 v140, s66, v185
	v_add_u32_e32 v156, s67, v185
	ds_read_b128 v[128:131], v140
	ds_read_b128 v[132:135], v140 offset:1024
	ds_read_b128 v[136:139], v140 offset:2048
	ds_read_b128 v[140:143], v140 offset:3072
	ds_read_b128 v[144:147], v156
	ds_read_b128 v[148:151], v156 offset:1024
	ds_read_b128 v[152:155], v156 offset:2048
	ds_read_b128 v[156:159], v156 offset:3072
	s_add_u32 s22, s28, 0xb0000
	s_addc_u32 s23, s29, 0
	s_mov_b32 m0, s34
	v_lshl_add_u64 v[232:233], s[22:23], 0, v[160:161]
	ds_read_b128 v[178:181], v191 offset:32768
	ds_read_b128 v[196:199], v191 offset:33792
	ds_read_b128 v[204:207], v191 offset:34816
	ds_read_b128 v[208:211], v191 offset:35840
	ds_read_b128 v[212:215], v191 offset:36864
	ds_read_b128 v[216:219], v191 offset:37888
	ds_read_b128 v[220:223], v191 offset:38912
	ds_read_b128 v[224:227], v191 offset:39936
	global_load_lds_dwordx4 v[232:233], off
	v_lshl_add_u64 v[232:233], s[22:23], 0, v[164:165]
	s_mov_b32 m0, s35
	s_nop 0
	global_load_lds_dwordx4 v[232:233], off
	s_waitcnt vmcnt(8)
	s_waitcnt lgkmcnt(0)
	s_barrier
	s_setprio 1
	s_waitcnt lgkmcnt(0)
	v_mfma_f32_16x16x32_bf16 v[124:127], v[128:131], v[178:181], v[124:127]
	v_mfma_f32_16x16x32_bf16 v[120:123], v[136:139], v[178:181], v[120:123]
	v_mfma_f32_16x16x32_bf16 v[108:111], v[128:131], v[204:207], v[108:111]
	v_mfma_f32_16x16x32_bf16 v[104:107], v[136:139], v[204:207], v[104:107]
	v_mfma_f32_16x16x32_bf16 v[92:95], v[128:131], v[212:215], v[92:95]
	v_mfma_f32_16x16x32_bf16 v[88:91], v[136:139], v[212:215], v[88:91]
	v_mfma_f32_16x16x32_bf16 v[76:79], v[128:131], v[220:223], v[76:79]
	v_mfma_f32_16x16x32_bf16 v[72:75], v[136:139], v[220:223], v[72:75]
	v_mfma_f32_16x16x32_bf16 v[124:127], v[132:135], v[196:199], v[124:127]
	v_mfma_f32_16x16x32_bf16 v[120:123], v[140:143], v[196:199], v[120:123]
	v_mfma_f32_16x16x32_bf16 v[108:111], v[132:135], v[208:211], v[108:111]
	v_mfma_f32_16x16x32_bf16 v[104:107], v[140:143], v[208:211], v[104:107]
	v_mfma_f32_16x16x32_bf16 v[92:95], v[132:135], v[216:219], v[92:95]
	v_mfma_f32_16x16x32_bf16 v[88:91], v[140:143], v[216:219], v[88:91]
	v_mfma_f32_16x16x32_bf16 v[76:79], v[132:135], v[224:227], v[76:79]
	v_mfma_f32_16x16x32_bf16 v[72:75], v[140:143], v[224:227], v[72:75]
	s_setprio 0
	s_setprio 1
	v_mfma_f32_16x16x32_bf16 v[116:119], v[144:147], v[178:181], v[116:119]
	v_mfma_f32_16x16x32_bf16 v[112:115], v[152:155], v[178:181], v[112:115]
	v_mfma_f32_16x16x32_bf16 v[100:103], v[144:147], v[204:207], v[100:103]
	v_mfma_f32_16x16x32_bf16 v[96:99], v[152:155], v[204:207], v[96:99]
	v_mfma_f32_16x16x32_bf16 v[84:87], v[144:147], v[212:215], v[84:87]
	v_mfma_f32_16x16x32_bf16 v[80:83], v[152:155], v[212:215], v[80:83]
	v_mfma_f32_16x16x32_bf16 v[68:71], v[144:147], v[220:223], v[68:71]
	v_mfma_f32_16x16x32_bf16 v[64:67], v[152:155], v[220:223], v[64:67]
	v_mfma_f32_16x16x32_bf16 v[116:119], v[148:151], v[196:199], v[116:119]
	v_mfma_f32_16x16x32_bf16 v[112:115], v[156:159], v[196:199], v[112:115]
	v_mfma_f32_16x16x32_bf16 v[100:103], v[148:151], v[208:211], v[100:103]
	v_mfma_f32_16x16x32_bf16 v[96:99], v[156:159], v[208:211], v[96:99]
	v_mfma_f32_16x16x32_bf16 v[84:87], v[148:151], v[216:219], v[84:87]
	v_mfma_f32_16x16x32_bf16 v[80:83], v[156:159], v[216:219], v[80:83]
	v_mfma_f32_16x16x32_bf16 v[68:71], v[148:151], v[224:227], v[68:71]
	v_mfma_f32_16x16x32_bf16 v[64:67], v[156:159], v[224:227], v[64:67]
	s_setprio 0
	s_barrier
; #define PG8_STAGE(bufoff, gbase, voff) do { _Pragma("unroll") for (int _i = 0; _i < 2; ++_i) \
;         __builtin_amdgcn_global_load_lds((const unsigned*)((const char*)(gbase) + (voff)[_i]), (PG8_LAS unsigned*)(lds + (bufoff) + ldsw + _i * 8192), 16, 0, 0); } while (0)
; #define PG8_LDA(dst, b, h) do { _Pragma("unroll") for (int m = 0; m < 4; ++m) _Pragma("unroll") for (int k = 0; k < 2; ++k) dst[m][k] = *(const PG8_LAS bf16x8*)(lds + PG8_SA(b, h) + aoff + m * 2048 + k * 1024); } while (0)
; #define PG8_MMA(ai, bj, At, Bt) do { __builtin_amdgcn_s_setprio(1); _Pragma("unroll") for (int m = 0; m < 4; ++m) _Pragma("unroll") for (int n = 0; n < 2; ++n) _Pragma("unroll") for (int k = 0; k < 2; ++k) \
;         acc[ai][bj][m][n] = __builtin_amdgcn_mfma_f32_16x16x32_bf16(Bt[n][k], At[m][k], acc[ai][bj][m][n], 0, 0, 0); __builtin_amdgcn_s_setprio(0); } while (0)
; #define PG8_WAIT_V(n) asm volatile("s_waitcnt vmcnt(" #n ")" ::: "memory")
; #define PG8_WAIT_L(n) asm volatile("s_waitcnt lgkmcnt(" #n ")" ::: "memory")
; #define PG8_BAR __builtin_amdgcn_s_barrier()
; #define PG8_SCHED __builtin_amdgcn_sched_barrier(0)
; template <class Epi, class Sched, bool ALIGN_EPI = false, bool SP2 = false>
; __device__ __forceinline__ void gemm_phase(PG8_LAS unsigned char* lds, const Gemm g, const Sched& S, const Epi& E) {
;     ...
;         for (int t = 0; t < nt; t += 2) {
;     ...
;             PG8_LDA(At, 1, 1); PG8_STAGE(PG8_SB(1, 0), b3, voffB); PG8_STAGE(PG8_SB(1, 1), b3 + hstep, voffB); PG8_STAGE(PG8_SA(1, 0), a3, voffA);
;             PG8_WAIT_V(8); PG8_WAIT_L(0); PG8_BAR; PG8_MMA(1, 0, At, B0); PG8_MMA(1, 1, At, B1); PG8_BAR; PG8_SCHED;
	s_add_i32 s22, s66, s30
	v_lshl_add_u64 v[182:183], v[182:183], 0, s[14:15]
	s_mov_b32 m0, s22
	ds_read_b128 v[178:181], v191 offset:49152
	ds_read_b128 v[196:199], v191 offset:50176
	ds_read_b128 v[204:207], v191 offset:51200
	ds_read_b128 v[208:211], v191 offset:52224
	ds_read_b128 v[212:215], v191 offset:53248
	ds_read_b128 v[216:219], v191 offset:54272
	ds_read_b128 v[220:223], v191 offset:55296
	ds_read_b128 v[224:227], v191 offset:56320
	global_load_lds_dwordx4 v[182:183], off
	s_add_i32 m0, s22, 0x2000
	s_add_u32 s22, s26, 0xb0080
	v_lshl_add_u64 v[182:183], v[200:201], 0, s[14:15]
	s_addc_u32 s23, s27, 0
	s_add_i32 s26, s67, s30
	global_load_lds_dwordx4 v[182:183], off
	v_lshl_add_u64 v[182:183], s[22:23], 0, v[162:163]
	s_mov_b32 m0, s26
	s_nop 0
	global_load_lds_dwordx4 v[182:183], off
	v_lshl_add_u64 v[182:183], s[22:23], 0, v[166:167]
	s_add_i32 m0, s26, 0x2000
	s_nop 0
	global_load_lds_dwordx4 v[182:183], off
	v_lshl_add_u64 v[182:183], v[228:229], 0, s[14:15]
	s_mov_b32 m0, s40
	s_nop 0
	global_load_lds_dwordx4 v[182:183], off
	v_lshl_add_u64 v[182:183], v[230:231], 0, s[14:15]
	s_mov_b32 m0, s41
	s_nop 0
	global_load_lds_dwordx4 v[182:183], off
	s_waitcnt vmcnt(8)
	s_waitcnt lgkmcnt(0)
	s_barrier
	s_setprio 1
	s_waitcnt lgkmcnt(0)
	v_mfma_f32_16x16x32_bf16 v[60:63], v[128:131], v[178:181], v[60:63]
	v_mfma_f32_16x16x32_bf16 v[56:59], v[136:139], v[178:181], v[56:59]
	v_mfma_f32_16x16x32_bf16 v[44:47], v[128:131], v[204:207], v[44:47]
	v_mfma_f32_16x16x32_bf16 v[40:43], v[136:139], v[204:207], v[40:43]
	v_mfma_f32_16x16x32_bf16 v[28:31], v[128:131], v[212:215], v[28:31]
	v_mfma_f32_16x16x32_bf16 v[24:27], v[136:139], v[212:215], v[24:27]
	v_mfma_f32_16x16x32_bf16 v[12:15], v[128:131], v[220:223], v[12:15]
	v_mfma_f32_16x16x32_bf16 v[8:11], v[136:139], v[220:223], v[8:11]
	v_mfma_f32_16x16x32_bf16 v[60:63], v[132:135], v[196:199], v[60:63]
	v_mfma_f32_16x16x32_bf16 v[56:59], v[140:143], v[196:199], v[56:59]
	v_mfma_f32_16x16x32_bf16 v[44:47], v[132:135], v[208:211], v[44:47]
	v_mfma_f32_16x16x32_bf16 v[40:43], v[140:143], v[208:211], v[40:43]
	v_mfma_f32_16x16x32_bf16 v[28:31], v[132:135], v[216:219], v[28:31]
	v_mfma_f32_16x16x32_bf16 v[24:27], v[140:143], v[216:219], v[24:27]
	v_mfma_f32_16x16x32_bf16 v[12:15], v[132:135], v[224:227], v[12:15]
	v_mfma_f32_16x16x32_bf16 v[8:11], v[140:143], v[224:227], v[8:11]
	s_setprio 0
	s_setprio 1
	v_mfma_f32_16x16x32_bf16 v[52:55], v[144:147], v[178:181], v[52:55]
	s_add_i32 s65, s65, 2
	s_add_u32 s62, s62, 0x100
	s_addc_u32 s63, s63, 0
	v_mfma_f32_16x16x32_bf16 v[48:51], v[152:155], v[178:181], v[48:51]
	v_mfma_f32_16x16x32_bf16 v[36:39], v[144:147], v[204:207], v[36:39]
	v_mfma_f32_16x16x32_bf16 v[32:35], v[152:155], v[204:207], v[32:35]
	v_mfma_f32_16x16x32_bf16 v[20:23], v[144:147], v[212:215], v[20:23]
	v_mfma_f32_16x16x32_bf16 v[16:19], v[152:155], v[212:215], v[16:19]
	v_mfma_f32_16x16x32_bf16 v[4:7], v[144:147], v[220:223], v[4:7]
	v_mfma_f32_16x16x32_bf16 v[0:3], v[152:155], v[220:223], v[0:3]
	v_mfma_f32_16x16x32_bf16 v[52:55], v[148:151], v[196:199], v[52:55]
	v_mfma_f32_16x16x32_bf16 v[48:51], v[156:159], v[196:199], v[48:51]
	v_mfma_f32_16x16x32_bf16 v[36:39], v[148:151], v[208:211], v[36:39]
	v_mfma_f32_16x16x32_bf16 v[32:35], v[156:159], v[208:211], v[32:35]
	v_mfma_f32_16x16x32_bf16 v[20:23], v[148:151], v[216:219], v[20:23]
	v_mfma_f32_16x16x32_bf16 v[16:19], v[156:159], v[216:219], v[16:19]
	v_mfma_f32_16x16x32_bf16 v[4:7], v[148:151], v[224:227], v[4:7]
	v_mfma_f32_16x16x32_bf16 v[0:3], v[156:159], v[224:227], v[0:3]
	s_setprio 0
	s_barrier
	s_cmp_gt_u32 s65, 41
	s_mov_b64 s[22:23], s[24:25]
	s_cbranch_scc0 .LBB0_908
	s_and_b64 vcc, exec, s[16:17]
	s_cbranch_vccz .LBB0_911
	s_barrier
